# hand-scheduled k-loops for all four big GEMMs (w_in, w_out, mlp up, mlp down) + scan priority 0 + scan wait deferral
# speedup vs baseline: 1.0043x; 1.0043x over previous
; DEV int tid_() { int t = __builtin_amdgcn_workitem_id_x(); asm volatile("" : "+v"(t)); return t; }
; template <class Epi>
; DEV void gemm_tile(const bf16_t* __restrict__ A, int lda, const bf16_t* __restrict__ Bt, int ldb, int K, int tm, int tn, char* smem, const Epi& epi) {
;     const int tid = tid_(), lane = tid & 63, wid = tid >> 6, wr = wid >> 1, wc = wid & 1, fr = lane & 15, fq = lane >> 4;
;     bf16_t* As = (bf16_t*)smem;
;     bf16_t* Bs = As + 2 * 128 * 64;
;     const int lrow = tid >> 3, lcc = (tid & 7) * 8, lsw = (((tid & 7) ^ (lrow & 7)) * 8);
;     const bf16_t* Ag = A + (size_t)(tm * 128 + lrow) * lda + lcc;
;     const bf16_t* Bg = Bt + (size_t)(tn * 128 + lrow) * ldb + lcc;
;     f32x4 acc[4][4];
; #pragma unroll
;     for (int m = 0; m < 4; ++m)
; #pragma unroll
;         for (int n = 0; n < 4; ++n) acc[m][n] = (f32x4){0.f, 0.f, 0.f, 0.f};
;     const int gsw = (((tid & 7) ^ (lrow & 7)) * 8);
;     const bf16_t* Ad = A + (size_t)(tm * 128 + lrow) * lda + gsw;
;     const bf16_t* Bd = Bt + (size_t)(tn * 128 + lrow) * ldb + gsw;
;     char* Asb = (char*)As; char* Bsb = (char*)Bs;
;     ...
;     const int nk = K >> 6;
;     G_DMA(0, 0);
;     asm volatile("s_waitcnt vmcnt(0)" ::: "memory");
;     __syncthreads();
; #pragma unroll 4
;     for (int kt = 0; kt < nk; ++kt) {
;         const int cur = kt & 1;
;         if (kt + 1 < nk) G_DMA(cur ^ 1, kt + 1);
; template <class Epi>
; DEV void gemm_phase(const bf16_t* A, int lda, const bf16_t* Bt, int ldb, int K, int ntm, int ntn, bool skip_ctx, char* smem, const Epi& epi) {
;     ...
;             if (q < fullq) { const int tb = q / (R * 8), r = q - tb * (R * 8); tm = r >> 3; tn = tb * 8 + (r & 7); }
;             else { const int q2 = q - fullq; tm = q2 / w; tn = nfb * 8 + (q2 - tm * w); }
;             tm += xcd * R;
;             if (skip_ctx && ((tm * 128) % TT) >= SEQ) continue;
.LBB0_162:
	s_lshr_b32 s43, s37, 3
	v_readlane_b32 s42, v253, 31
	s_add_i32 s43, s43, s42
	s_lshl_b32 s42, s43, 7
	s_mul_hi_u32 s44, s42, 0x38e38e39
	s_lshr_b32 s44, s44, 9
	s_mulk_i32 s44, 0x900
	s_sub_i32 s44, s42, s44
	s_cmpk_gt_u32 s44, 0x7ff
	s_cselect_b64 s[44:45], -1, 0
	s_and_b64 s[44:45], s[54:55], s[44:45]
	s_and_b64 vcc, exec, s[44:45]
	s_cbranch_vccnz .LBB0_161
	v_mov_b32_e32 v10, v163
	s_and_b32 s44, s36, 0x380
	s_waitcnt vmcnt(10)
	v_ashrrev_i32_e32 v0, 3, v10
	v_add_u32_e32 v2, s42, v0
	v_ashrrev_i32_e32 v3, 31, v2
	v_add_u32_e32 v4, s44, v0
	v_xor_b32_e32 v0, v0, v10
	v_ashrrev_i32_e32 v5, 31, v4
	v_lshlrev_b64 v[2:3], 11, v[2:3]
	v_lshlrev_b32_e32 v0, 4, v0
	s_waitcnt vmcnt(5)
	v_lshl_add_u32 v22, v10, 4, 16
	v_lshl_add_u64 v[2:3], s[26:27], 0, v[2:3]
	v_lshlrev_b64 v[4:5], 11, v[4:5]
	v_and_b32_e32 v0, 0x70, v0
	s_waitcnt vmcnt(4)
	v_add_u32_e32 v21, 0x8000, v22
	v_readfirstlane_b32 s65, v22
	v_lshl_add_u64 v[8:9], s[38:39], 0, v[4:5]
	v_lshl_add_u64 v[4:5], v[2:3], 0, v[0:1]
	s_mov_b32 m0, s65
	v_readfirstlane_b32 s53, v21
	v_add_u32_e32 v23, 0x1000, v22
	v_lshl_add_u64 v[2:3], v[8:9], 0, v[0:1]
	global_load_lds_dwordx4 v[4:5], off
	s_mov_b32 m0, s53
	s_mov_b64 s[90:91], 0x10000
	v_readfirstlane_b32 s62, v23
	v_add_u32_e32 v24, 0x9000, v22
	global_load_lds_dwordx4 v[2:3], off
	v_lshl_add_u64 v[8:9], v[4:5], 0, s[90:91]
	s_mov_b32 m0, s62
	v_readfirstlane_b32 s63, v24
	v_add_u32_e32 v25, 0x2000, v22
	global_load_lds_dwordx4 v[8:9], off
	v_lshl_add_u64 v[8:9], v[2:3], 0, s[90:91]
	s_mov_b32 m0, s63
	s_mov_b64 s[92:93], 0x20000
	v_readfirstlane_b32 s64, v25
	v_add_u32_e32 v26, 0xa000, v22
	global_load_lds_dwordx4 v[8:9], off
	v_lshl_add_u64 v[8:9], v[4:5], 0, s[92:93]
	s_mov_b32 m0, s64
	v_readfirstlane_b32 s84, v26
	v_add_u32_e32 v27, 0x3000, v22
	global_load_lds_dwordx4 v[8:9], off
	v_lshl_add_u64 v[8:9], v[2:3], 0, s[92:93]
	s_mov_b32 m0, s84
	s_mov_b64 s[0:1], 0x30000
	v_readfirstlane_b32 s85, v27
	v_add_u32_e32 v28, 0xb000, v22
	global_load_lds_dwordx4 v[8:9], off
	v_lshl_add_u64 v[8:9], v[4:5], 0, s[0:1]
	s_mov_b32 m0, s85
	v_readfirstlane_b32 s86, v28
	global_load_lds_dwordx4 v[8:9], off
	v_lshl_add_u64 v[8:9], v[2:3], 0, s[0:1]
	s_mov_b32 m0, s86
	v_and_b32_e32 v7, 15, v10
	global_load_lds_dwordx4 v[8:9], off
	v_ashrrev_i32_e32 v8, 7, v10
	v_lshlrev_b32_e32 v9, 13, v8
	v_lshlrev_b32_e32 v12, 7, v7
	v_bfe_u32 v6, v10, 6, 1
	v_lshrrev_b32_e32 v11, 4, v10
	v_add3_u32 v29, 16, v9, v12
	v_and_b32_e32 v9, 7, v10
	v_bfe_u32 v0, v10, 4, 2
	v_bitop3_b32 v10, v11, v9, 3 bitop3:0x6c
	v_lshlrev_b32_e32 v11, 13, v6
	v_add3_u32 v110, 16, v11, v12
	v_add_u32_e32 v11, 0x4000, v22
	s_mov_b64 s[46:47], 0x80
	v_add_u32_e32 v12, 0xc000, v22
	v_readfirstlane_b32 s49, v11
	v_lshl_add_u64 v[14:15], v[4:5], 0, s[46:47]
	s_mov_b32 m0, s49
	v_readfirstlane_b32 s45, v12
	v_add_u32_e32 v13, 0x5000, v22
	s_waitcnt vmcnt(0)
	s_waitcnt vmcnt(0) lgkmcnt(0)
	s_barrier
	v_writelane_b32 v255, s88, 24
	v_writelane_b32 v255, s89, 25
	v_writelane_b32 v255, s90, 26
	v_writelane_b32 v255, s91, 27
	v_writelane_b32 v255, s92, 28
	v_writelane_b32 v255, s93, 29
	v_writelane_b32 v255, s94, 30
	v_writelane_b32 v255, s95, 31
	v_readfirstlane_b32 s88, v4
	v_readfirstlane_b32 s89, v5
	v_readfirstlane_b32 s90, v2
	v_readfirstlane_b32 s91, v3
	v_lshl_add_u32 v225, v163, 4, 16
	s_and_b32 s88, s88, 0xffffff80
	s_and_b32 s90, s90, 0xffffff80
	v_readfirstlane_b32 s93, v225
	v_subrev_u32_e32 v184, s88, v4
	v_subrev_u32_e32 v217, s90, v2
	v_add_u32_e32 v214, 0x10000, v184
	v_add_u32_e32 v218, 0x10000, v217
	v_add_u32_e32 v215, 0x20000, v184
	v_add_u32_e32 v219, 0x20000, v217
	v_add_u32_e32 v216, 0x30000, v184
	v_add_u32_e32 v220, 0x30000, v217
	s_add_u32 s94, s93, 0x4000
	s_add_u32 s88, s88, 0x80
	s_addc_u32 s89, s89, 0
	s_add_u32 s90, s90, 0x80
	s_addc_u32 s91, s91, 0
	v_and_b32_e32 v225, 15, v163
	v_lshlrev_b32_e32 v225, 7, v225
	v_bfe_u32 v226, v163, 4, 2
	v_and_b32_e32 v227, 7, v163
	v_xor_b32_e32 v226, v226, v227
	v_lshlrev_b32_e32 v227, 4, v226
	v_xor_b32_e32 v226, 4, v226
	v_lshlrev_b32_e32 v226, 4, v226
	v_lshrrev_b32_e32 v221, 7, v163
	v_lshl_add_u32 v221, v221, 13, v225
	v_add_u32_e32 v221, 16, v221
	v_bfe_u32 v223, v163, 6, 1
	v_lshl_add_u32 v223, v223, 13, v225
	v_add_u32_e32 v223, 16, v223
	v_add_u32_e32 v222, v221, v226
	v_add_u32_e32 v224, v223, v226
	v_add_u32_e32 v221, v221, v227
	v_add_u32_e32 v223, v223, v227
	v_mov_b32_e32 v62, 0
	v_mov_b32_e32 v63, 0
	v_mov_b32_e32 v64, 0
	v_mov_b32_e32 v65, 0
	v_mov_b32_e32 v66, 0
	v_mov_b32_e32 v67, 0
	v_mov_b32_e32 v68, 0
	v_mov_b32_e32 v69, 0
	v_mov_b32_e32 v70, 0
	v_mov_b32_e32 v71, 0
	v_mov_b32_e32 v72, 0
	v_mov_b32_e32 v73, 0
	v_mov_b32_e32 v2, 0
	v_mov_b32_e32 v3, 0
	v_mov_b32_e32 v4, 0
	v_mov_b32_e32 v5, 0
	v_mov_b32_e32 v18, 0
	v_mov_b32_e32 v19, 0
	v_mov_b32_e32 v20, 0
	v_mov_b32_e32 v21, 0
	v_mov_b32_e32 v28, 0
	v_mov_b32_e32 v29, 0
	v_mov_b32_e32 v30, 0
	v_mov_b32_e32 v31, 0
	v_mov_b32_e32 v56, 0
	v_mov_b32_e32 v57, 0
	v_mov_b32_e32 v58, 0
	v_mov_b32_e32 v59, 0
	v_mov_b32_e32 v10, 0
	v_mov_b32_e32 v11, 0
	v_mov_b32_e32 v12, 0
	v_mov_b32_e32 v13, 0
	v_mov_b32_e32 v22, 0
	v_mov_b32_e32 v23, 0
	v_mov_b32_e32 v24, 0
	v_mov_b32_e32 v25, 0
	v_mov_b32_e32 v32, 0
	v_mov_b32_e32 v33, 0
	v_mov_b32_e32 v34, 0
	v_mov_b32_e32 v35, 0
	v_mov_b32_e32 v74, 0
	v_mov_b32_e32 v75, 0
	v_mov_b32_e32 v76, 0
	v_mov_b32_e32 v77, 0
	v_mov_b32_e32 v36, 0
	v_mov_b32_e32 v37, 0
	v_mov_b32_e32 v38, 0
	v_mov_b32_e32 v39, 0
	v_mov_b32_e32 v44, 0
	v_mov_b32_e32 v45, 0
	v_mov_b32_e32 v46, 0
	v_mov_b32_e32 v47, 0
	v_mov_b32_e32 v48, 0
	v_mov_b32_e32 v49, 0
	v_mov_b32_e32 v50, 0
	v_mov_b32_e32 v51, 0
	v_mov_b32_e32 v52, 0
	v_mov_b32_e32 v53, 0
	v_mov_b32_e32 v54, 0
	v_mov_b32_e32 v55, 0
	v_mov_b32_e32 v14, 0
	v_mov_b32_e32 v15, 0
	v_mov_b32_e32 v16, 0
	v_mov_b32_e32 v17, 0
	s_mov_b32 m0, s94
	s_nop 0
	global_load_lds_dwordx4 v184, s[88:89]
	s_add_u32 m0, m0, 0x1000
	s_nop 0
	global_load_lds_dwordx4 v214, s[88:89]
	s_add_u32 m0, m0, 0x1000
	s_nop 0
	global_load_lds_dwordx4 v215, s[88:89]
	s_add_u32 m0, m0, 0x1000
	s_nop 0
	global_load_lds_dwordx4 v216, s[88:89]
	s_add_u32 m0, m0, 0x5000
	s_nop 0
	global_load_lds_dwordx4 v217, s[90:91]
	s_add_u32 m0, m0, 0x1000
	s_nop 0
	global_load_lds_dwordx4 v218, s[90:91]
	s_add_u32 m0, m0, 0x1000
	s_nop 0
	global_load_lds_dwordx4 v219, s[90:91]
	s_add_u32 m0, m0, 0x1000
	s_nop 0
	global_load_lds_dwordx4 v220, s[90:91]
	s_add_u32 s88, s88, 0x80
	s_addc_u32 s89, s89, 0
	s_add_u32 s90, s90, 0x80
	s_addc_u32 s91, s91, 0
	ds_read_b128 v[126:129], v221
	ds_read_b128 v[130:133], v221 offset:2048
	ds_read_b128 v[134:137], v221 offset:4096
	ds_read_b128 v[138:141], v221 offset:6144
	ds_read_b128 v[142:145], v223 offset:32768
	ds_read_b128 v[146:149], v223 offset:34816
	ds_read_b128 v[150:153], v223 offset:36864
	ds_read_b128 v[154:157], v223 offset:38912
	s_movk_i32 s92, 7
; #define G_MMA(ks_) __builtin_amdgcn_s_setprio(1); _Pragma("unroll") for (int m = 0; m < 4; ++m) \
;         _Pragma("unroll") for (int n = 0; n < 4; ++n) acc[m][n] = __builtin_amdgcn_mfma_f32_16x16x32_bf16(bfv##ks_[n], af##ks_[m], acc[m][n], 0, 0, 0); __builtin_amdgcn_s_setprio(0);
; template <class Epi>
; DEV void gemm_tile(const bf16_t* __restrict__ A, int lda, const bf16_t* __restrict__ Bt, int ldb, int K, int tm, int tn, char* smem, const Epi& epi) {
;     ...
;     const int nk = K >> 6;
;     G_DMA(0, 0);
;     asm volatile("s_waitcnt vmcnt(0)" ::: "memory");
;     __syncthreads();
; #pragma unroll 4
;     for (int kt = 0; kt < nk; ++kt) {
;         const int cur = kt & 1;
;         if (kt + 1 < nk) G_DMA(cur ^ 1, kt + 1);
;         {
;             G_FRAGS(cur, 0)
;             G_MMA(0)
;             G_FRAGS(cur, 1)
;             G_MMA(1)
;         }
;         asm volatile("s_waitcnt vmcnt(0)" ::: "memory");
;         __syncthreads();
.Lgemm_out_loop:
	ds_read_b128 v[158:161], v222
	ds_read_b128 v[164:167], v222 offset:2048
	ds_read_b128 v[168:171], v222 offset:4096
	ds_read_b128 v[172:175], v222 offset:6144
	ds_read_b128 v[176:179], v224 offset:32768
	ds_read_b128 v[180:183], v224 offset:34816
	ds_read_b128 v[192:195], v224 offset:36864
	ds_read_b128 v[210:213], v224 offset:38912
	s_setprio 1
	s_waitcnt lgkmcnt(8)
	v_mfma_f32_16x16x32_bf16 v[62:65], v[142:145], v[126:129], v[62:65]
	v_mfma_f32_16x16x32_bf16 v[66:69], v[146:149], v[126:129], v[66:69]
	v_mfma_f32_16x16x32_bf16 v[70:73], v[150:153], v[126:129], v[70:73]
	v_mfma_f32_16x16x32_bf16 v[2:5], v[154:157], v[126:129], v[2:5]
	v_mfma_f32_16x16x32_bf16 v[18:21], v[142:145], v[130:133], v[18:21]
	v_mfma_f32_16x16x32_bf16 v[28:31], v[146:149], v[130:133], v[28:31]
	v_mfma_f32_16x16x32_bf16 v[56:59], v[150:153], v[130:133], v[56:59]
	v_mfma_f32_16x16x32_bf16 v[10:13], v[154:157], v[130:133], v[10:13]
	v_mfma_f32_16x16x32_bf16 v[22:25], v[142:145], v[134:137], v[22:25]
	v_mfma_f32_16x16x32_bf16 v[32:35], v[146:149], v[134:137], v[32:35]
	v_mfma_f32_16x16x32_bf16 v[74:77], v[150:153], v[134:137], v[74:77]
	v_mfma_f32_16x16x32_bf16 v[36:39], v[154:157], v[134:137], v[36:39]
	v_mfma_f32_16x16x32_bf16 v[44:47], v[142:145], v[138:141], v[44:47]
	v_mfma_f32_16x16x32_bf16 v[48:51], v[146:149], v[138:141], v[48:51]
	v_mfma_f32_16x16x32_bf16 v[52:55], v[150:153], v[138:141], v[52:55]
	v_mfma_f32_16x16x32_bf16 v[14:17], v[154:157], v[138:141], v[14:17]
	s_setprio 0
	s_waitcnt vmcnt(0) lgkmcnt(0)
	s_barrier
	ds_read_b128 v[126:129], v221 offset:16384
	ds_read_b128 v[130:133], v221 offset:18432
	ds_read_b128 v[134:137], v221 offset:20480
	ds_read_b128 v[138:141], v221 offset:22528
	ds_read_b128 v[142:145], v223 offset:49152
	ds_read_b128 v[146:149], v223 offset:51200
	ds_read_b128 v[150:153], v223 offset:53248
	ds_read_b128 v[154:157], v223 offset:55296
	s_setprio 1
	s_mov_b32 m0, s93
	v_mfma_f32_16x16x32_bf16 v[62:65], v[176:179], v[158:161], v[62:65]
	global_load_lds_dwordx4 v184, s[88:89]
	s_add_u32 m0, m0, 0x1000
	v_mfma_f32_16x16x32_bf16 v[66:69], v[180:183], v[158:161], v[66:69]
	global_load_lds_dwordx4 v214, s[88:89]
	s_add_u32 m0, m0, 0x1000
	v_mfma_f32_16x16x32_bf16 v[70:73], v[192:195], v[158:161], v[70:73]
	global_load_lds_dwordx4 v215, s[88:89]
	s_add_u32 m0, m0, 0x1000
	v_mfma_f32_16x16x32_bf16 v[2:5], v[210:213], v[158:161], v[2:5]
	global_load_lds_dwordx4 v216, s[88:89]
	s_add_u32 m0, m0, 0x5000
	v_mfma_f32_16x16x32_bf16 v[18:21], v[176:179], v[164:167], v[18:21]
	global_load_lds_dwordx4 v217, s[90:91]
	s_add_u32 m0, m0, 0x1000
	v_mfma_f32_16x16x32_bf16 v[28:31], v[180:183], v[164:167], v[28:31]
	global_load_lds_dwordx4 v218, s[90:91]
	s_add_u32 m0, m0, 0x1000
	v_mfma_f32_16x16x32_bf16 v[56:59], v[192:195], v[164:167], v[56:59]
	global_load_lds_dwordx4 v219, s[90:91]
	s_add_u32 m0, m0, 0x1000
	v_mfma_f32_16x16x32_bf16 v[10:13], v[210:213], v[164:167], v[10:13]
	global_load_lds_dwordx4 v220, s[90:91]
	v_mfma_f32_16x16x32_bf16 v[22:25], v[176:179], v[168:171], v[22:25]
	s_add_u32 s88, s88, 0x80
	v_mfma_f32_16x16x32_bf16 v[32:35], v[180:183], v[168:171], v[32:35]
	s_addc_u32 s89, s89, 0
	v_mfma_f32_16x16x32_bf16 v[74:77], v[192:195], v[168:171], v[74:77]
	s_add_u32 s90, s90, 0x80
	v_mfma_f32_16x16x32_bf16 v[36:39], v[210:213], v[168:171], v[36:39]
	s_addc_u32 s91, s91, 0
	v_mfma_f32_16x16x32_bf16 v[44:47], v[176:179], v[172:175], v[44:47]
	v_mfma_f32_16x16x32_bf16 v[48:51], v[180:183], v[172:175], v[48:51]
	v_mfma_f32_16x16x32_bf16 v[52:55], v[192:195], v[172:175], v[52:55]
	v_mfma_f32_16x16x32_bf16 v[14:17], v[210:213], v[172:175], v[14:17]
	s_setprio 0
	ds_read_b128 v[158:161], v222 offset:16384
	ds_read_b128 v[164:167], v222 offset:18432
	ds_read_b128 v[168:171], v222 offset:20480
	ds_read_b128 v[172:175], v222 offset:22528
	ds_read_b128 v[176:179], v224 offset:49152
	ds_read_b128 v[180:183], v224 offset:51200
	ds_read_b128 v[192:195], v224 offset:53248
	ds_read_b128 v[210:213], v224 offset:55296
	s_setprio 1
	s_waitcnt lgkmcnt(8)
	v_mfma_f32_16x16x32_bf16 v[62:65], v[142:145], v[126:129], v[62:65]
	v_mfma_f32_16x16x32_bf16 v[66:69], v[146:149], v[126:129], v[66:69]
	v_mfma_f32_16x16x32_bf16 v[70:73], v[150:153], v[126:129], v[70:73]
	v_mfma_f32_16x16x32_bf16 v[2:5], v[154:157], v[126:129], v[2:5]
	v_mfma_f32_16x16x32_bf16 v[18:21], v[142:145], v[130:133], v[18:21]
	v_mfma_f32_16x16x32_bf16 v[28:31], v[146:149], v[130:133], v[28:31]
	v_mfma_f32_16x16x32_bf16 v[56:59], v[150:153], v[130:133], v[56:59]
	v_mfma_f32_16x16x32_bf16 v[10:13], v[154:157], v[130:133], v[10:13]
	v_mfma_f32_16x16x32_bf16 v[22:25], v[142:145], v[134:137], v[22:25]
	v_mfma_f32_16x16x32_bf16 v[32:35], v[146:149], v[134:137], v[32:35]
	v_mfma_f32_16x16x32_bf16 v[74:77], v[150:153], v[134:137], v[74:77]
	v_mfma_f32_16x16x32_bf16 v[36:39], v[154:157], v[134:137], v[36:39]
	v_mfma_f32_16x16x32_bf16 v[44:47], v[142:145], v[138:141], v[44:47]
	v_mfma_f32_16x16x32_bf16 v[48:51], v[146:149], v[138:141], v[48:51]
	v_mfma_f32_16x16x32_bf16 v[52:55], v[150:153], v[138:141], v[52:55]
	v_mfma_f32_16x16x32_bf16 v[14:17], v[154:157], v[138:141], v[14:17]
	s_setprio 0
	s_waitcnt vmcnt(0) lgkmcnt(0)
	s_barrier
; #define G_MMA(ks_) __builtin_amdgcn_s_setprio(1); _Pragma("unroll") for (int m = 0; m < 4; ++m) \
;         _Pragma("unroll") for (int n = 0; n < 4; ++n) acc[m][n] = __builtin_amdgcn_mfma_f32_16x16x32_bf16(bfv##ks_[n], af##ks_[m], acc[m][n], 0, 0, 0); __builtin_amdgcn_s_setprio(0);
; template <class Epi>
; DEV void gemm_tile(const bf16_t* __restrict__ A, int lda, const bf16_t* __restrict__ Bt, int ldb, int K, int tm, int tn, char* smem, const Epi& epi) {
;     ...
;     const int nk = K >> 6;
;     G_DMA(0, 0);
;     asm volatile("s_waitcnt vmcnt(0)" ::: "memory");
;     __syncthreads();
; #pragma unroll 4
;     for (int kt = 0; kt < nk; ++kt) {
;         const int cur = kt & 1;
;         if (kt + 1 < nk) G_DMA(cur ^ 1, kt + 1);
;         {
;             G_FRAGS(cur, 0)
;             G_MMA(0)
;             G_FRAGS(cur, 1)
;             G_MMA(1)
;         }
;         asm volatile("s_waitcnt vmcnt(0)" ::: "memory");
;         __syncthreads();
	ds_read_b128 v[126:129], v221
	ds_read_b128 v[130:133], v221 offset:2048
	ds_read_b128 v[134:137], v221 offset:4096
	ds_read_b128 v[138:141], v221 offset:6144
	ds_read_b128 v[142:145], v223 offset:32768
	ds_read_b128 v[146:149], v223 offset:34816
	ds_read_b128 v[150:153], v223 offset:36864
	ds_read_b128 v[154:157], v223 offset:38912
	s_setprio 1
	s_mov_b32 m0, s94
	v_mfma_f32_16x16x32_bf16 v[62:65], v[176:179], v[158:161], v[62:65]
	global_load_lds_dwordx4 v184, s[88:89]
	s_add_u32 m0, m0, 0x1000
	v_mfma_f32_16x16x32_bf16 v[66:69], v[180:183], v[158:161], v[66:69]
	global_load_lds_dwordx4 v214, s[88:89]
	s_add_u32 m0, m0, 0x1000
	v_mfma_f32_16x16x32_bf16 v[70:73], v[192:195], v[158:161], v[70:73]
	global_load_lds_dwordx4 v215, s[88:89]
	s_add_u32 m0, m0, 0x1000
	v_mfma_f32_16x16x32_bf16 v[2:5], v[210:213], v[158:161], v[2:5]
	global_load_lds_dwordx4 v216, s[88:89]
	s_add_u32 m0, m0, 0x5000
	v_mfma_f32_16x16x32_bf16 v[18:21], v[176:179], v[164:167], v[18:21]
	global_load_lds_dwordx4 v217, s[90:91]
	s_add_u32 m0, m0, 0x1000
	v_mfma_f32_16x16x32_bf16 v[28:31], v[180:183], v[164:167], v[28:31]
	global_load_lds_dwordx4 v218, s[90:91]
	s_add_u32 m0, m0, 0x1000
	v_mfma_f32_16x16x32_bf16 v[56:59], v[192:195], v[164:167], v[56:59]
	global_load_lds_dwordx4 v219, s[90:91]
	s_add_u32 m0, m0, 0x1000
	v_mfma_f32_16x16x32_bf16 v[10:13], v[210:213], v[164:167], v[10:13]
	global_load_lds_dwordx4 v220, s[90:91]
	v_mfma_f32_16x16x32_bf16 v[22:25], v[176:179], v[168:171], v[22:25]
	s_add_u32 s88, s88, 0x80
	v_mfma_f32_16x16x32_bf16 v[32:35], v[180:183], v[168:171], v[32:35]
	s_addc_u32 s89, s89, 0
	v_mfma_f32_16x16x32_bf16 v[74:77], v[192:195], v[168:171], v[74:77]
	s_add_u32 s90, s90, 0x80
	v_mfma_f32_16x16x32_bf16 v[36:39], v[210:213], v[168:171], v[36:39]
	s_addc_u32 s91, s91, 0
	v_mfma_f32_16x16x32_bf16 v[44:47], v[176:179], v[172:175], v[44:47]
	v_mfma_f32_16x16x32_bf16 v[48:51], v[180:183], v[172:175], v[48:51]
	v_mfma_f32_16x16x32_bf16 v[52:55], v[192:195], v[172:175], v[52:55]
	v_mfma_f32_16x16x32_bf16 v[14:17], v[210:213], v[172:175], v[14:17]
	s_setprio 0
	s_sub_u32 s92, s92, 1
	s_cmp_lg_u32 s92, 0
	s_cbranch_scc1 .Lgemm_out_loop
	ds_read_b128 v[158:161], v222
	ds_read_b128 v[164:167], v222 offset:2048
	ds_read_b128 v[168:171], v222 offset:4096
	ds_read_b128 v[172:175], v222 offset:6144
	ds_read_b128 v[176:179], v224 offset:32768
	ds_read_b128 v[180:183], v224 offset:34816
	ds_read_b128 v[192:195], v224 offset:36864
	ds_read_b128 v[210:213], v224 offset:38912
	s_setprio 1
	s_waitcnt lgkmcnt(8)
	v_mfma_f32_16x16x32_bf16 v[62:65], v[142:145], v[126:129], v[62:65]
	v_mfma_f32_16x16x32_bf16 v[66:69], v[146:149], v[126:129], v[66:69]
	v_mfma_f32_16x16x32_bf16 v[70:73], v[150:153], v[126:129], v[70:73]
	v_mfma_f32_16x16x32_bf16 v[2:5], v[154:157], v[126:129], v[2:5]
	v_mfma_f32_16x16x32_bf16 v[18:21], v[142:145], v[130:133], v[18:21]
	v_mfma_f32_16x16x32_bf16 v[28:31], v[146:149], v[130:133], v[28:31]
	v_mfma_f32_16x16x32_bf16 v[56:59], v[150:153], v[130:133], v[56:59]
	v_mfma_f32_16x16x32_bf16 v[10:13], v[154:157], v[130:133], v[10:13]
	v_mfma_f32_16x16x32_bf16 v[22:25], v[142:145], v[134:137], v[22:25]
	v_mfma_f32_16x16x32_bf16 v[32:35], v[146:149], v[134:137], v[32:35]
	v_mfma_f32_16x16x32_bf16 v[74:77], v[150:153], v[134:137], v[74:77]
	v_mfma_f32_16x16x32_bf16 v[36:39], v[154:157], v[134:137], v[36:39]
	v_mfma_f32_16x16x32_bf16 v[44:47], v[142:145], v[138:141], v[44:47]
	v_mfma_f32_16x16x32_bf16 v[48:51], v[146:149], v[138:141], v[48:51]
	v_mfma_f32_16x16x32_bf16 v[52:55], v[150:153], v[138:141], v[52:55]
	v_mfma_f32_16x16x32_bf16 v[14:17], v[154:157], v[138:141], v[14:17]
	s_setprio 0
	s_waitcnt vmcnt(0) lgkmcnt(0)
	s_barrier
	ds_read_b128 v[126:129], v221 offset:16384
	ds_read_b128 v[130:133], v221 offset:18432
	ds_read_b128 v[134:137], v221 offset:20480
	ds_read_b128 v[138:141], v221 offset:22528
	ds_read_b128 v[142:145], v223 offset:49152
	ds_read_b128 v[146:149], v223 offset:51200
	ds_read_b128 v[150:153], v223 offset:53248
	ds_read_b128 v[154:157], v223 offset:55296
	s_setprio 1
	v_mfma_f32_16x16x32_bf16 v[62:65], v[176:179], v[158:161], v[62:65]
	v_mfma_f32_16x16x32_bf16 v[66:69], v[180:183], v[158:161], v[66:69]
	v_mfma_f32_16x16x32_bf16 v[70:73], v[192:195], v[158:161], v[70:73]
	v_mfma_f32_16x16x32_bf16 v[2:5], v[210:213], v[158:161], v[2:5]
	v_mfma_f32_16x16x32_bf16 v[18:21], v[176:179], v[164:167], v[18:21]
	v_mfma_f32_16x16x32_bf16 v[28:31], v[180:183], v[164:167], v[28:31]
	v_mfma_f32_16x16x32_bf16 v[56:59], v[192:195], v[164:167], v[56:59]
	v_mfma_f32_16x16x32_bf16 v[10:13], v[210:213], v[164:167], v[10:13]
	v_mfma_f32_16x16x32_bf16 v[22:25], v[176:179], v[168:171], v[22:25]
	v_mfma_f32_16x16x32_bf16 v[32:35], v[180:183], v[168:171], v[32:35]
	v_mfma_f32_16x16x32_bf16 v[74:77], v[192:195], v[168:171], v[74:77]
	v_mfma_f32_16x16x32_bf16 v[36:39], v[210:213], v[168:171], v[36:39]
	v_mfma_f32_16x16x32_bf16 v[44:47], v[176:179], v[172:175], v[44:47]
	v_mfma_f32_16x16x32_bf16 v[48:51], v[180:183], v[172:175], v[48:51]
	v_mfma_f32_16x16x32_bf16 v[52:55], v[192:195], v[172:175], v[52:55]
	v_mfma_f32_16x16x32_bf16 v[14:17], v[210:213], v[172:175], v[14:17]
	s_setprio 0
	ds_read_b128 v[158:161], v222 offset:16384
	ds_read_b128 v[164:167], v222 offset:18432
	ds_read_b128 v[168:171], v222 offset:20480
	ds_read_b128 v[172:175], v222 offset:22528
	ds_read_b128 v[176:179], v224 offset:49152
	ds_read_b128 v[180:183], v224 offset:51200
	ds_read_b128 v[192:195], v224 offset:53248
	ds_read_b128 v[210:213], v224 offset:55296
	s_setprio 1
	s_waitcnt lgkmcnt(8)
	v_mfma_f32_16x16x32_bf16 v[62:65], v[142:145], v[126:129], v[62:65]
	v_mfma_f32_16x16x32_bf16 v[66:69], v[146:149], v[126:129], v[66:69]
	v_mfma_f32_16x16x32_bf16 v[70:73], v[150:153], v[126:129], v[70:73]
	v_mfma_f32_16x16x32_bf16 v[2:5], v[154:157], v[126:129], v[2:5]
	v_mfma_f32_16x16x32_bf16 v[18:21], v[142:145], v[130:133], v[18:21]
	v_mfma_f32_16x16x32_bf16 v[28:31], v[146:149], v[130:133], v[28:31]
	v_mfma_f32_16x16x32_bf16 v[56:59], v[150:153], v[130:133], v[56:59]
	v_mfma_f32_16x16x32_bf16 v[10:13], v[154:157], v[130:133], v[10:13]
	v_mfma_f32_16x16x32_bf16 v[22:25], v[142:145], v[134:137], v[22:25]
	v_mfma_f32_16x16x32_bf16 v[32:35], v[146:149], v[134:137], v[32:35]
	v_mfma_f32_16x16x32_bf16 v[74:77], v[150:153], v[134:137], v[74:77]
	v_mfma_f32_16x16x32_bf16 v[36:39], v[154:157], v[134:137], v[36:39]
	v_mfma_f32_16x16x32_bf16 v[44:47], v[142:145], v[138:141], v[44:47]
	v_mfma_f32_16x16x32_bf16 v[48:51], v[146:149], v[138:141], v[48:51]
	v_mfma_f32_16x16x32_bf16 v[52:55], v[150:153], v[138:141], v[52:55]
	v_mfma_f32_16x16x32_bf16 v[14:17], v[154:157], v[138:141], v[14:17]
	s_setprio 0
	s_waitcnt lgkmcnt(0)
	s_barrier
; DEV int tid_() { int t = __builtin_amdgcn_workitem_id_x(); asm volatile("" : "+v"(t)); return t; }
; template <class Epi>
; DEV void gemm_tile(const bf16_t* __restrict__ A, int lda, const bf16_t* __restrict__ Bt, int ldb, int K, int tm, int tn, char* smem, const Epi& epi) {
;     ...
;     float* Ct = (float*)smem;
; #pragma unroll
;     for (int m = 0; m < 4; ++m)
; #pragma unroll
;         for (int n = 0; n < 4; ++n) *(f32x4*)(Ct + (wr * 64 + m * 16 + fr) * CP + wc * 64 + n * 16 + fq * 4) = acc[m][n];
;     __syncthreads();
;     DEV void operator()(int tm, int tn, const float* Ct) const {
;         const int row0 = tm * 128, b = row0 / TT, tt0 = row0 - b * TT;
;         const int tid = tid_(), c = (tid & 31) << 2, rb = tid >> 5;
;         const f32x4 g = *(const f32x4*)(mod + (size_t)(tt0 < SEQ ? b : 32) * 6144 + goff + tn * 128 + c);
;         float* x0 = xrow(*p, row0) + tn * 128 + c;
;         const float* xs = from_in ? xrow_in(*p, row0) + tn * 128 + c : x0;
; #pragma unroll
;         for (int it0 = 0; it0 < 16; it0 += 8) {
;             f32x4 xv[8];
; #pragma unroll
;             for (int u = 0; u < 8; ++u) xv[u] = *(const f32x4*)(xs + (size_t)(rb + 8 * (it0 + u)) * D);
	s_setprio 1
	v_mfma_f32_16x16x32_bf16 v[62:65], v[176:179], v[158:161], v[62:65]
	v_mfma_f32_16x16x32_bf16 v[66:69], v[180:183], v[158:161], v[66:69]
	v_mfma_f32_16x16x32_bf16 v[70:73], v[192:195], v[158:161], v[70:73]
	v_mfma_f32_16x16x32_bf16 v[2:5], v[210:213], v[158:161], v[2:5]
	v_mfma_f32_16x16x32_bf16 v[18:21], v[176:179], v[164:167], v[18:21]
	v_mfma_f32_16x16x32_bf16 v[28:31], v[180:183], v[164:167], v[28:31]
	v_mfma_f32_16x16x32_bf16 v[56:59], v[192:195], v[164:167], v[56:59]
	v_mfma_f32_16x16x32_bf16 v[10:13], v[210:213], v[164:167], v[10:13]
	v_mfma_f32_16x16x32_bf16 v[22:25], v[176:179], v[168:171], v[22:25]
	v_mfma_f32_16x16x32_bf16 v[32:35], v[180:183], v[168:171], v[32:35]
	v_mfma_f32_16x16x32_bf16 v[74:77], v[192:195], v[168:171], v[74:77]
	v_mfma_f32_16x16x32_bf16 v[36:39], v[210:213], v[168:171], v[36:39]
	v_mfma_f32_16x16x32_bf16 v[44:47], v[176:179], v[172:175], v[44:47]
	v_mfma_f32_16x16x32_bf16 v[48:51], v[180:183], v[172:175], v[48:51]
	v_mfma_f32_16x16x32_bf16 v[52:55], v[192:195], v[172:175], v[52:55]
	v_mfma_f32_16x16x32_bf16 v[14:17], v[210:213], v[172:175], v[14:17]
	s_setprio 0
	v_readlane_b32 s88, v255, 24
	v_readlane_b32 s89, v255, 25
	v_readlane_b32 s90, v255, 26
	v_readlane_b32 s91, v255, 27
	v_readlane_b32 s92, v255, 28
	v_readlane_b32 s93, v255, 29
	v_readlane_b32 s94, v255, 30
	v_readlane_b32 s95, v255, 31
	s_nop 7
	s_nop 1
	s_mul_hi_u32 s43, s43, 0x38e38e39
	s_lshr_b32 s94, s43, 2
	s_mul_i32 s43, s94, 0xfffff700
	s_add_i32 s48, s43, s42
	s_cmpk_lt_i32 s48, 0x800
	s_cselect_b64 s[42:43], -1, 0
	s_mul_i32 s45, s94, 0x6000
	s_and_b64 s[46:47], s[42:43], exec
	v_lshl_or_b32 v7, v8, 6, v7
	s_cselect_b32 s45, s45, 0xc0000
	v_lshl_add_u32 v6, v6, 8, 16
	v_lshlrev_b32_e32 v0, 4, v0
	v_mul_lo_u32 v7, v7, s58
	s_add_u32 s45, s10, s45
	v_add3_u32 v0, v6, v0, v7
	v_mov_b32_e32 v6, v163
	s_addc_u32 s46, s11, 0
	s_lshl_b32 s47, s44, 2
	s_waitcnt vmcnt(0)
	s_barrier
	ds_write_b128 v0, v[62:65]
	ds_write_b128 v0, v[66:69] offset:64
	ds_write_b128 v0, v[70:73] offset:128
	ds_write_b128 v0, v[2:5] offset:192
	ds_write_b128 v0, v[18:21] offset:8448
	ds_write_b128 v0, v[28:31] offset:8512
	ds_write_b128 v0, v[56:59] offset:8576
	ds_write_b128 v0, v[10:13] offset:8640
	ds_write_b128 v0, v[22:25] offset:16896
	ds_write_b128 v0, v[32:35] offset:16960
	ds_write_b128 v0, v[74:77] offset:17024
	ds_write_b128 v0, v[36:39] offset:17088
	ds_write_b128 v0, v[44:47] offset:25344
	ds_write_b128 v0, v[48:51] offset:25408
	ds_write_b128 v0, v[52:55] offset:25472
	ds_write_b128 v0, v[14:17] offset:25536
	s_waitcnt lgkmcnt(0)
	s_barrier
	s_add_u32 s44, s45, s47
	v_lshlrev_b32_e32 v0, 4, v6
	s_addc_u32 s45, s46, 0
	v_and_b32_e32 v0, 0x1f0, v0
	v_lshl_add_u64 v[2:3], s[44:45], 0, v[0:1]
	s_movk_i32 s44, 0x2000
	s_add_i32 s46, s48, 0xfffff800
	s_ashr_i32 s49, s48, 31
	v_add_co_u32_e32 v2, vcc, s44, v2
	s_and_b64 s[44:45], s[42:43], exec
	v_readlane_b32 s64, v251, 1
	v_readlane_b32 s67, v251, 4
	v_readlane_b32 s44, v251, 36
	s_cselect_b32 s50, 23, 20
	v_readlane_b32 s66, v251, 3
	s_cselect_b32 s51, s67, s44
	v_readlane_b32 s44, v251, 35
	s_cselect_b32 s52, s66, s44
	s_cselect_b32 s45, s49, 0
	s_cselect_b32 s44, s48, s46
	s_lshl_b32 s46, s94, s50
	s_add_u32 s46, s52, s46
	s_addc_u32 s48, s51, 0
	s_lshl_b64 s[44:45], s[44:45], 12
	s_add_u32 s49, s46, s44
	s_addc_u32 s51, s48, s45
	s_and_b64 s[42:43], s[42:43], exec
	s_cselect_b32 s52, s69, s73
	s_cselect_b32 s53, s68, s72
	s_lshl_b64 s[42:43], s[94:95], s50
	s_add_u32 s50, s53, s42
	s_addc_u32 s52, s52, s43
	s_and_b64 s[42:43], s[6:7], exec
	s_cselect_b32 s43, s46, s50
	s_cselect_b32 s42, s48, s52
	s_add_u32 s44, s43, s44
	s_addc_u32 s45, s42, s45
	s_add_u32 s42, s49, s47
	s_addc_u32 s43, s51, 0
	v_lshl_add_u64 v[14:15], s[42:43], 0, v[0:1]
	v_ashrrev_i32_e32 v48, 5, v6
	s_add_u32 s42, s44, s47
	s_addc_u32 s43, s45, 0
	v_ashrrev_i32_e32 v49, 31, v48
	v_lshl_add_u64 v[16:17], s[42:43], 0, v[0:1]
	v_lshlrev_b64 v[18:19], 12, v[48:49]
	v_addc_co_u32_e32 v3, vcc, 0, v3, vcc
	v_lshl_add_u64 v[6:7], v[16:17], 0, v[18:19]
	global_load_dwordx4 v[2:5], v[2:3], off
	s_mov_b64 s[42:43], 0x8000
	global_load_dwordx4 v[24:27], v[6:7], off
	v_lshl_add_u64 v[52:53], v[18:19], 0, s[42:43]
	v_lshl_add_u64 v[6:7], v[16:17], 0, v[52:53]
	global_load_dwordx4 v[28:31], v[6:7], off
	v_lshl_add_u64 v[54:55], v[18:19], 0, s[90:91]
	v_lshl_add_u64 v[6:7], v[16:17], 0, v[54:55]
	global_load_dwordx4 v[32:35], v[6:7], off
	s_mov_b64 s[42:43], 0x18000
	v_lshl_add_u64 v[56:57], v[18:19], 0, s[42:43]
	v_lshl_add_u64 v[6:7], v[16:17], 0, v[56:57]
	global_load_dwordx4 v[36:39], v[6:7], off
	v_lshl_add_u64 v[58:59], v[18:19], 0, s[92:93]
	v_lshl_add_u64 v[6:7], v[16:17], 0, v[58:59]
	global_load_dwordx4 v[40:43], v[6:7], off
	s_mov_b64 s[42:43], 0x28000
	v_lshl_add_u64 v[60:61], v[18:19], 0, s[42:43]
	v_lshl_add_u64 v[6:7], v[16:17], 0, v[60:61]
	global_load_dwordx4 v[44:47], v[6:7], off
	v_lshl_add_u64 v[22:23], v[18:19], 0, s[0:1]
	v_lshl_add_u64 v[6:7], v[16:17], 0, v[22:23]
	global_load_dwordx4 v[10:13], v[6:7], off
	s_mov_b64 s[0:1], 0x38000
	v_lshl_add_u64 v[20:21], v[18:19], 0, s[0:1]
	v_lshl_add_u64 v[6:7], v[16:17], 0, v[20:21]
	global_load_dwordx4 v[6:9], v[6:7], off
	v_mul_lo_u32 v48, v48, s58
	v_add3_u32 v0, 16, v0, v48
	ds_read_b128 v[48:51], v0
	v_lshl_add_u64 v[22:23], v[14:15], 0, v[22:23]
	s_mov_b64 s[0:1], 0x40000
	s_mov_b64 s[42:43], 0x48000
	v_readlane_b32 s65, v251, 2
	s_waitcnt vmcnt(7) lgkmcnt(0)
;     DEV void operator()(int tm, int tn, const float* Ct) const {
;     ...
; #pragma unroll
;         for (int it0 = 0; it0 < 16; it0 += 8) {
;             f32x4 xv[8];
; #pragma unroll
;             for (int u = 0; u < 8; ++u) xv[u] = *(const f32x4*)(xs + (size_t)(rb + 8 * (it0 + u)) * D);
; #pragma unroll
;             for (int u = 0; u < 8; ++u) { const int r = rb + 8 * (it0 + u); *(f32x4*)(x0 + (size_t)r * D) = xv[u] + g * *(const f32x4*)(Ct + r * CP + c); }
;         }
	v_pk_fma_f32 v[26:27], v[4:5], v[50:51], v[26:27]
	v_pk_fma_f32 v[24:25], v[2:3], v[48:49], v[24:25]
	v_lshl_add_u64 v[48:49], v[14:15], 0, v[18:19]
	global_store_dwordx4 v[48:49], v[24:27], off
	ds_read_b128 v[24:27], v0 offset:4224
	v_lshl_add_u64 v[50:51], v[18:19], 0, s[0:1]
	s_mov_b64 s[0:1], 0x50000
	s_waitcnt vmcnt(7) lgkmcnt(0)
	v_pk_fma_f32 v[26:27], v[4:5], v[26:27], v[30:31]
	v_pk_fma_f32 v[24:25], v[2:3], v[24:25], v[28:29]
	v_lshl_add_u64 v[28:29], v[14:15], 0, v[52:53]
	global_store_dwordx4 v[28:29], v[24:27], off
	ds_read_b128 v[24:27], v0 offset:8448
	v_lshl_add_u64 v[28:29], v[14:15], 0, v[54:55]
	v_lshl_add_u64 v[52:53], v[18:19], 0, s[42:43]
	v_lshl_add_u64 v[54:55], v[18:19], 0, s[0:1]
	s_mov_b64 s[0:1], 0x58000
	s_waitcnt vmcnt(7) lgkmcnt(0)
	v_pk_fma_f32 v[26:27], v[4:5], v[26:27], v[34:35]
	v_pk_fma_f32 v[24:25], v[2:3], v[24:25], v[32:33]
	global_store_dwordx4 v[28:29], v[24:27], off
	ds_read_b128 v[24:27], v0 offset:12672
	v_lshl_add_u64 v[28:29], v[14:15], 0, v[56:57]
	v_lshl_add_u64 v[56:57], v[18:19], 0, s[0:1]
	s_mov_b64 s[0:1], 0x60000
	s_waitcnt vmcnt(7) lgkmcnt(0)
	v_pk_fma_f32 v[26:27], v[4:5], v[26:27], v[38:39]
	v_pk_fma_f32 v[24:25], v[2:3], v[24:25], v[36:37]
	global_store_dwordx4 v[28:29], v[24:27], off
	ds_read_b128 v[24:27], v0 offset:16896
	v_lshl_add_u64 v[28:29], v[14:15], 0, v[58:59]
	v_lshl_add_u64 v[58:59], v[18:19], 0, s[0:1]
	s_mov_b64 s[0:1], 0x68000
	s_waitcnt vmcnt(7) lgkmcnt(0)
	v_pk_fma_f32 v[26:27], v[4:5], v[26:27], v[42:43]
	v_pk_fma_f32 v[24:25], v[2:3], v[24:25], v[40:41]
	global_store_dwordx4 v[28:29], v[24:27], off
	ds_read_b128 v[24:27], v0 offset:21120
	v_lshl_add_u64 v[28:29], v[14:15], 0, v[60:61]
	v_lshl_add_u64 v[60:61], v[18:19], 0, s[0:1]
	s_mov_b64 s[0:1], 0x70000
	s_waitcnt vmcnt(7) lgkmcnt(0)
	v_pk_fma_f32 v[26:27], v[4:5], v[26:27], v[46:47]
	v_pk_fma_f32 v[24:25], v[2:3], v[24:25], v[44:45]
	global_store_dwordx4 v[28:29], v[24:27], off
	ds_read_b128 v[24:27], v0 offset:25344
	ds_read_b128 v[46:49], v0 offset:33792
	s_waitcnt vmcnt(7) lgkmcnt(1)
	v_pk_fma_f32 v[12:13], v[4:5], v[26:27], v[12:13]
	v_pk_fma_f32 v[10:11], v[2:3], v[24:25], v[10:11]
	global_store_dwordx4 v[22:23], v[10:13], off
	ds_read_b128 v[10:13], v0 offset:29568
	s_waitcnt vmcnt(7) lgkmcnt(0)
	v_pk_fma_f32 v[8:9], v[4:5], v[12:13], v[8:9]
	v_pk_fma_f32 v[6:7], v[2:3], v[10:11], v[6:7]
	v_lshl_add_u64 v[10:11], v[14:15], 0, v[20:21]
	global_store_dwordx4 v[10:11], v[6:9], off
	v_lshl_add_u64 v[20:21], v[18:19], 0, s[0:1]
	s_mov_b64 s[0:1], 0x78000
	v_lshl_add_u64 v[6:7], v[16:17], 0, v[50:51]
	global_load_dwordx4 v[22:25], v[6:7], off
	v_lshl_add_u64 v[6:7], v[16:17], 0, v[52:53]
	global_load_dwordx4 v[26:29], v[6:7], off
	v_lshl_add_u64 v[6:7], v[16:17], 0, v[54:55]
	global_load_dwordx4 v[30:33], v[6:7], off
	v_lshl_add_u64 v[6:7], v[16:17], 0, v[56:57]
	global_load_dwordx4 v[34:37], v[6:7], off
	v_lshl_add_u64 v[6:7], v[16:17], 0, v[58:59]
	global_load_dwordx4 v[38:41], v[6:7], off
	v_lshl_add_u64 v[6:7], v[16:17], 0, v[60:61]
	global_load_dwordx4 v[42:45], v[6:7], off
	v_lshl_add_u64 v[6:7], v[16:17], 0, v[20:21]
	global_load_dwordx4 v[10:13], v[6:7], off
	v_lshl_add_u64 v[18:19], v[18:19], 0, s[0:1]
	v_lshl_add_u64 v[6:7], v[16:17], 0, v[18:19]
	global_load_dwordx4 v[6:9], v[6:7], off
	v_lshl_add_u64 v[16:17], v[14:15], 0, v[50:51]
	s_waitcnt vmcnt(7)
	v_pk_fma_f32 v[24:25], v[4:5], v[48:49], v[24:25]
	v_pk_fma_f32 v[22:23], v[2:3], v[46:47], v[22:23]
	global_store_dwordx4 v[16:17], v[22:25], off
	ds_read_b128 v[22:25], v0 offset:38016
	v_lshl_add_u64 v[16:17], v[14:15], 0, v[52:53]
	s_waitcnt vmcnt(7) lgkmcnt(0)
	v_pk_fma_f32 v[24:25], v[4:5], v[24:25], v[28:29]
	v_pk_fma_f32 v[22:23], v[2:3], v[22:23], v[26:27]
	global_store_dwordx4 v[16:17], v[22:25], off
	ds_read_b128 v[22:25], v0 offset:42240
	v_lshl_add_u64 v[16:17], v[14:15], 0, v[54:55]
	s_waitcnt vmcnt(7) lgkmcnt(0)
	v_pk_fma_f32 v[24:25], v[4:5], v[24:25], v[32:33]
	v_pk_fma_f32 v[22:23], v[2:3], v[22:23], v[30:31]
	global_store_dwordx4 v[16:17], v[22:25], off
	ds_read_b128 v[22:25], v0 offset:46464
	v_lshl_add_u64 v[16:17], v[14:15], 0, v[56:57]
	s_waitcnt vmcnt(7) lgkmcnt(0)
	v_pk_fma_f32 v[24:25], v[4:5], v[24:25], v[36:37]
	v_pk_fma_f32 v[22:23], v[2:3], v[22:23], v[34:35]
	global_store_dwordx4 v[16:17], v[22:25], off
	ds_read_b128 v[22:25], v0 offset:50688
	v_lshl_add_u64 v[16:17], v[14:15], 0, v[58:59]
	s_waitcnt vmcnt(7) lgkmcnt(0)
	v_pk_fma_f32 v[24:25], v[4:5], v[24:25], v[40:41]
	v_pk_fma_f32 v[22:23], v[2:3], v[22:23], v[38:39]
	global_store_dwordx4 v[16:17], v[22:25], off
	ds_read_b128 v[22:25], v0 offset:54912
	v_lshl_add_u64 v[16:17], v[14:15], 0, v[60:61]
	s_waitcnt vmcnt(7) lgkmcnt(0)
	v_pk_fma_f32 v[24:25], v[4:5], v[24:25], v[44:45]
	v_pk_fma_f32 v[22:23], v[2:3], v[22:23], v[42:43]
	global_store_dwordx4 v[16:17], v[22:25], off
	ds_read_b128 v[22:25], v0 offset:59136
	v_lshl_add_u64 v[16:17], v[14:15], 0, v[20:21]
	s_waitcnt vmcnt(7) lgkmcnt(0)
	v_pk_fma_f32 v[12:13], v[4:5], v[24:25], v[12:13]
	v_pk_fma_f32 v[10:11], v[2:3], v[22:23], v[10:11]
	global_store_dwordx4 v[16:17], v[10:13], off
	ds_read_b128 v[10:13], v0 offset:63360
	s_waitcnt vmcnt(7) lgkmcnt(0)
	v_pk_fma_f32 v[4:5], v[4:5], v[12:13], v[8:9]
	v_pk_fma_f32 v[2:3], v[2:3], v[10:11], v[6:7]
	v_lshl_add_u64 v[6:7], v[14:15], 0, v[18:19]
	global_store_dwordx4 v[6:7], v[2:5], off
	s_barrier
	s_branch .LBB0_161

; DEV int tid_() { int t = __builtin_amdgcn_workitem_id_x(); asm volatile("" : "+v"(t)); return t; }
; template <class Epi>
; DEV void gemm_tile(const bf16_t* __restrict__ A, int lda, const bf16_t* __restrict__ Bt, int ldb, int K, int tm, int tn, char* smem, const Epi& epi) {
;     const int tid = tid_(), lane = tid & 63, wid = tid >> 6, wr = wid >> 1, wc = wid & 1, fr = lane & 15, fq = lane >> 4;
;     bf16_t* As = (bf16_t*)smem;
;     bf16_t* Bs = As + 2 * 128 * 64;
;     const int lrow = tid >> 3, lcc = (tid & 7) * 8, lsw = (((tid & 7) ^ (lrow & 7)) * 8);
;     const bf16_t* Ag = A + (size_t)(tm * 128 + lrow) * lda + lcc;
;     const bf16_t* Bg = Bt + (size_t)(tn * 128 + lrow) * ldb + lcc;
;     f32x4 acc[4][4];
; #pragma unroll
;     for (int m = 0; m < 4; ++m)
; #pragma unroll
;         for (int n = 0; n < 4; ++n) acc[m][n] = (f32x4){0.f, 0.f, 0.f, 0.f};
;     const int gsw = (((tid & 7) ^ (lrow & 7)) * 8);
;     const bf16_t* Ad = A + (size_t)(tm * 128 + lrow) * lda + gsw;
;     const bf16_t* Bd = Bt + (size_t)(tn * 128 + lrow) * ldb + gsw;
;     char* Asb = (char*)As; char* Bsb = (char*)Bs;
;     ...
;     const int nk = K >> 6;
;     G_DMA(0, 0);
;     asm volatile("s_waitcnt vmcnt(0)" ::: "memory");
;     __syncthreads();
; #pragma unroll 4
;     for (int kt = 0; kt < nk; ++kt) {
;         const int cur = kt & 1;
;         if (kt + 1 < nk) G_DMA(cur ^ 1, kt + 1);
; template <class Epi>
; DEV void gemm_phase(const bf16_t* A, int lda, const bf16_t* Bt, int ldb, int K, int ntm, int ntn, bool skip_ctx, char* smem, const Epi& epi) {
;     ...
;             if (q < fullq) { const int tb = q / (R * 8), r = q - tb * (R * 8); tm = r >> 3; tn = tb * 8 + (r & 7); }
;             else { const int q2 = q - fullq; tm = q2 / w; tn = nfb * 8 + (q2 - tm * w); }
;             tm += xcd * R;
;             if (skip_ctx && ((tm * 128) % TT) >= SEQ) continue;
.LBB0_179:
	s_lshr_b32 s39, s37, 3
	v_readlane_b32 s38, v253, 31
	s_add_i32 s39, s39, s38
	s_lshl_b32 s38, s39, 7
	s_mul_hi_u32 s42, s38, 0x38e38e39
	s_lshr_b32 s42, s42, 9
	s_mulk_i32 s42, 0x900
	s_sub_i32 s42, s38, s42
	s_cmpk_gt_u32 s42, 0x7ff
	s_cselect_b64 s[42:43], -1, 0
	s_and_b64 s[42:43], s[54:55], s[42:43]
	s_and_b64 vcc, exec, s[42:43]
	s_cbranch_vccnz .LBB0_178
	v_mov_b32_e32 v10, v163
	s_and_b32 s42, s36, 0x380
	s_waitcnt vmcnt(10)
	v_ashrrev_i32_e32 v0, 3, v10
	v_readlane_b32 s44, v251, 27
	v_add_u32_e32 v4, s38, v0
	v_add_u32_e32 v8, s42, v0
	v_xor_b32_e32 v0, v0, v10
	v_readlane_b32 s45, v251, 28
	v_lshlrev_b32_e32 v0, 4, v0
	v_lshl_add_u32 v14, v10, 4, 16
	v_mov_b64_e32 v[2:3], s[44:45]
	v_mad_i64_i32 v[2:3], s[44:45], v4, s29, v[2:3]
	v_mov_b64_e32 v[4:5], s[0:1]
	v_and_b32_e32 v0, 0x70, v0
	v_add_u32_e32 v13, 0x8000, v14
	v_readfirstlane_b32 s63, v14
	v_mad_i64_i32 v[8:9], s[44:45], v8, s29, v[4:5]
	v_lshl_add_u64 v[4:5], v[2:3], 0, v[0:1]
	s_mov_b32 m0, s63
	v_readfirstlane_b32 s51, v13
	v_add_u32_e32 v15, 0x1000, v14
	v_lshl_add_u64 v[2:3], v[8:9], 0, v[0:1]
	global_load_lds_dwordx4 v[4:5], off
	s_mov_b32 m0, s51
	s_mov_b64 s[44:45], 0x2c000
	v_readfirstlane_b32 s52, v15
	v_add_u32_e32 v16, 0x9000, v14
	global_load_lds_dwordx4 v[2:3], off
	v_lshl_add_u64 v[8:9], v[4:5], 0, s[44:45]
	s_mov_b32 m0, s52
	v_readfirstlane_b32 s53, v16
	v_add_u32_e32 v17, 0x2000, v14
	global_load_lds_dwordx4 v[8:9], off
	v_lshl_add_u64 v[8:9], v[2:3], 0, s[44:45]
	s_mov_b32 m0, s53
	s_mov_b64 s[44:45], 0x58000
	v_readfirstlane_b32 s62, v17
	s_waitcnt vmcnt(0)
	v_add_u32_e32 v18, 0xa000, v14
	global_load_lds_dwordx4 v[8:9], off
	v_lshl_add_u64 v[8:9], v[4:5], 0, s[44:45]
	s_mov_b32 m0, s62
	v_readfirstlane_b32 s64, v18
	v_add_u32_e32 v19, 0x3000, v14
	global_load_lds_dwordx4 v[8:9], off
	v_lshl_add_u64 v[8:9], v[2:3], 0, s[44:45]
	s_mov_b32 m0, s64
	s_mov_b64 s[44:45], 0x84000
	v_readfirstlane_b32 s65, v19
	v_add_u32_e32 v20, 0xb000, v14
	global_load_lds_dwordx4 v[8:9], off
	v_lshl_add_u64 v[8:9], v[4:5], 0, s[44:45]
	s_mov_b32 m0, s65
	v_readfirstlane_b32 s84, v20
	global_load_lds_dwordx4 v[8:9], off
	v_lshl_add_u64 v[8:9], v[2:3], 0, s[44:45]
	s_mov_b32 m0, s84
	v_and_b32_e32 v7, 15, v10
	global_load_lds_dwordx4 v[8:9], off
	v_ashrrev_i32_e32 v8, 7, v10
	v_bfe_u32 v6, v10, 6, 1
	v_lshlrev_b32_e32 v9, 13, v8
	v_lshlrev_b32_e32 v12, 7, v7
	v_add_u32_e32 v21, 0x4000, v14
	v_lshrrev_b32_e32 v11, 4, v10
	v_bfe_u32 v0, v10, 4, 2
	v_add3_u32 v29, 16, v9, v12
	v_and_b32_e32 v9, 7, v10
	v_lshlrev_b32_e32 v10, 13, v6
	s_mov_b64 s[44:45], 0x80
	v_add_u32_e32 v22, 0xc000, v14
	v_readfirstlane_b32 s47, v21
	v_bitop3_b32 v30, v11, v9, 3 bitop3:0x6c
	v_add3_u32 v12, 16, v10, v12
	v_lshl_add_u64 v[10:11], v[4:5], 0, s[44:45]
	s_mov_b32 m0, s47
	v_readfirstlane_b32 s43, v22
	s_waitcnt vmcnt(0)
	s_waitcnt vmcnt(0) lgkmcnt(0)
	s_barrier
	v_writelane_b32 v255, s88, 24
	v_writelane_b32 v255, s89, 25
	v_writelane_b32 v255, s90, 26
	v_writelane_b32 v255, s91, 27
	v_writelane_b32 v255, s92, 28
	v_writelane_b32 v255, s93, 29
	v_writelane_b32 v255, s94, 30
	v_writelane_b32 v255, s95, 31
	v_readfirstlane_b32 s88, v4
	v_readfirstlane_b32 s89, v5
	v_readfirstlane_b32 s90, v2
	v_readfirstlane_b32 s91, v3
	v_lshl_add_u32 v225, v163, 4, 16
	s_and_b32 s88, s88, 0xffffff80
	s_and_b32 s90, s90, 0xffffff80
	v_readfirstlane_b32 s93, v225
	v_subrev_u32_e32 v184, s88, v4
	v_subrev_u32_e32 v217, s90, v2
	v_add_u32_e32 v214, 0x2c000, v184
	v_add_u32_e32 v218, 0x2c000, v217
	v_add_u32_e32 v215, 0x58000, v184
	v_add_u32_e32 v219, 0x58000, v217
	v_add_u32_e32 v216, 0x84000, v184
	v_add_u32_e32 v220, 0x84000, v217
	s_add_u32 s94, s93, 0x4000
	s_add_u32 s88, s88, 0x80
	s_addc_u32 s89, s89, 0
	s_add_u32 s90, s90, 0x80
	s_addc_u32 s91, s91, 0
	v_and_b32_e32 v225, 15, v163
	v_lshlrev_b32_e32 v225, 7, v225
	v_bfe_u32 v226, v163, 4, 2
	v_and_b32_e32 v227, 7, v163
	v_xor_b32_e32 v226, v226, v227
	v_lshlrev_b32_e32 v227, 4, v226
	v_xor_b32_e32 v226, 4, v226
	v_lshlrev_b32_e32 v226, 4, v226
	v_lshrrev_b32_e32 v221, 7, v163
	v_lshl_add_u32 v221, v221, 13, v225
	v_add_u32_e32 v221, 16, v221
	v_bfe_u32 v223, v163, 6, 1
	v_lshl_add_u32 v223, v223, 13, v225
	v_add_u32_e32 v223, 16, v223
	v_add_u32_e32 v222, v221, v226
	v_add_u32_e32 v224, v223, v226
	v_add_u32_e32 v221, v221, v227
	v_add_u32_e32 v223, v223, v227
	v_mov_b32_e32 v62, 0
	v_mov_b32_e32 v63, 0
	v_mov_b32_e32 v64, 0
	v_mov_b32_e32 v65, 0
	v_mov_b32_e32 v66, 0
	v_mov_b32_e32 v67, 0
	v_mov_b32_e32 v68, 0
	v_mov_b32_e32 v69, 0
	v_mov_b32_e32 v70, 0
	v_mov_b32_e32 v71, 0
	v_mov_b32_e32 v72, 0
	v_mov_b32_e32 v73, 0
	v_mov_b32_e32 v2, 0
	v_mov_b32_e32 v3, 0
	v_mov_b32_e32 v4, 0
	v_mov_b32_e32 v5, 0
	v_mov_b32_e32 v14, 0
	v_mov_b32_e32 v15, 0
	v_mov_b32_e32 v16, 0
	v_mov_b32_e32 v17, 0
	v_mov_b32_e32 v22, 0
	v_mov_b32_e32 v23, 0
	v_mov_b32_e32 v24, 0
	v_mov_b32_e32 v25, 0
	v_mov_b32_e32 v30, 0
	v_mov_b32_e32 v31, 0
	v_mov_b32_e32 v32, 0
	v_mov_b32_e32 v33, 0
	v_mov_b32_e32 v18, 0
	v_mov_b32_e32 v19, 0
	v_mov_b32_e32 v20, 0
	v_mov_b32_e32 v21, 0
	v_mov_b32_e32 v26, 0
	v_mov_b32_e32 v27, 0
	v_mov_b32_e32 v28, 0
	v_mov_b32_e32 v29, 0
	v_mov_b32_e32 v34, 0
	v_mov_b32_e32 v35, 0
	v_mov_b32_e32 v36, 0
	v_mov_b32_e32 v37, 0
	v_mov_b32_e32 v58, 0
	v_mov_b32_e32 v59, 0
	v_mov_b32_e32 v60, 0
	v_mov_b32_e32 v61, 0
	v_mov_b32_e32 v38, 0
	v_mov_b32_e32 v39, 0
	v_mov_b32_e32 v40, 0
	v_mov_b32_e32 v41, 0
	v_mov_b32_e32 v46, 0
	v_mov_b32_e32 v47, 0
	v_mov_b32_e32 v48, 0
	v_mov_b32_e32 v49, 0
	v_mov_b32_e32 v50, 0
	v_mov_b32_e32 v51, 0
	v_mov_b32_e32 v52, 0
	v_mov_b32_e32 v53, 0
	v_mov_b32_e32 v54, 0
	v_mov_b32_e32 v55, 0
	v_mov_b32_e32 v56, 0
	v_mov_b32_e32 v57, 0
	v_mov_b32_e32 v10, 0
	v_mov_b32_e32 v11, 0
	v_mov_b32_e32 v12, 0
	v_mov_b32_e32 v13, 0
	s_mov_b32 m0, s94
	s_nop 0
	global_load_lds_dwordx4 v184, s[88:89]
	s_add_u32 m0, m0, 0x1000
	s_nop 0
	global_load_lds_dwordx4 v214, s[88:89]
	s_add_u32 m0, m0, 0x1000
	s_nop 0
	global_load_lds_dwordx4 v215, s[88:89]
	s_add_u32 m0, m0, 0x1000
	s_nop 0
	global_load_lds_dwordx4 v216, s[88:89]
	s_add_u32 m0, m0, 0x5000
	s_nop 0
	global_load_lds_dwordx4 v217, s[90:91]
	s_add_u32 m0, m0, 0x1000
	s_nop 0
	global_load_lds_dwordx4 v218, s[90:91]
	s_add_u32 m0, m0, 0x1000
	s_nop 0
	global_load_lds_dwordx4 v219, s[90:91]
	s_add_u32 m0, m0, 0x1000
	s_nop 0
	global_load_lds_dwordx4 v220, s[90:91]
	s_add_u32 s88, s88, 0x80
	s_addc_u32 s89, s89, 0
	s_add_u32 s90, s90, 0x80
	s_addc_u32 s91, s91, 0
	ds_read_b128 v[126:129], v221
	ds_read_b128 v[130:133], v221 offset:2048
	ds_read_b128 v[134:137], v221 offset:4096
	ds_read_b128 v[138:141], v221 offset:6144
	ds_read_b128 v[142:145], v223 offset:32768
	ds_read_b128 v[146:149], v223 offset:34816
	ds_read_b128 v[150:153], v223 offset:36864
	ds_read_b128 v[154:157], v223 offset:38912
	s_movk_i32 s92, 21
; #define G_MMA(ks_) __builtin_amdgcn_s_setprio(1); _Pragma("unroll") for (int m = 0; m < 4; ++m) \
;         _Pragma("unroll") for (int n = 0; n < 4; ++n) acc[m][n] = __builtin_amdgcn_mfma_f32_16x16x32_bf16(bfv##ks_[n], af##ks_[m], acc[m][n], 0, 0, 0); __builtin_amdgcn_s_setprio(0);
; template <class Epi>
; DEV void gemm_tile(const bf16_t* __restrict__ A, int lda, const bf16_t* __restrict__ Bt, int ldb, int K, int tm, int tn, char* smem, const Epi& epi) {
;     ...
;     const int nk = K >> 6;
;     G_DMA(0, 0);
;     asm volatile("s_waitcnt vmcnt(0)" ::: "memory");
;     __syncthreads();
; #pragma unroll 4
;     for (int kt = 0; kt < nk; ++kt) {
;         const int cur = kt & 1;
;         if (kt + 1 < nk) G_DMA(cur ^ 1, kt + 1);
;         {
;             G_FRAGS(cur, 0)
;             G_MMA(0)
;             G_FRAGS(cur, 1)
;             G_MMA(1)
;         }
;         asm volatile("s_waitcnt vmcnt(0)" ::: "memory");
;         __syncthreads();
.Lgemm_down_loop:
	ds_read_b128 v[158:161], v222
	ds_read_b128 v[164:167], v222 offset:2048
	ds_read_b128 v[168:171], v222 offset:4096
	ds_read_b128 v[172:175], v222 offset:6144
	ds_read_b128 v[176:179], v224 offset:32768
	ds_read_b128 v[180:183], v224 offset:34816
	ds_read_b128 v[192:195], v224 offset:36864
	ds_read_b128 v[210:213], v224 offset:38912
	s_setprio 1
	s_waitcnt lgkmcnt(8)
	v_mfma_f32_16x16x32_bf16 v[62:65], v[142:145], v[126:129], v[62:65]
	v_mfma_f32_16x16x32_bf16 v[66:69], v[146:149], v[126:129], v[66:69]
	v_mfma_f32_16x16x32_bf16 v[70:73], v[150:153], v[126:129], v[70:73]
	v_mfma_f32_16x16x32_bf16 v[2:5], v[154:157], v[126:129], v[2:5]
	v_mfma_f32_16x16x32_bf16 v[14:17], v[142:145], v[130:133], v[14:17]
	v_mfma_f32_16x16x32_bf16 v[22:25], v[146:149], v[130:133], v[22:25]
	v_mfma_f32_16x16x32_bf16 v[30:33], v[150:153], v[130:133], v[30:33]
	v_mfma_f32_16x16x32_bf16 v[18:21], v[154:157], v[130:133], v[18:21]
	v_mfma_f32_16x16x32_bf16 v[26:29], v[142:145], v[134:137], v[26:29]
	v_mfma_f32_16x16x32_bf16 v[34:37], v[146:149], v[134:137], v[34:37]
	v_mfma_f32_16x16x32_bf16 v[58:61], v[150:153], v[134:137], v[58:61]
	v_mfma_f32_16x16x32_bf16 v[38:41], v[154:157], v[134:137], v[38:41]
	v_mfma_f32_16x16x32_bf16 v[46:49], v[142:145], v[138:141], v[46:49]
	v_mfma_f32_16x16x32_bf16 v[50:53], v[146:149], v[138:141], v[50:53]
	v_mfma_f32_16x16x32_bf16 v[54:57], v[150:153], v[138:141], v[54:57]
	v_mfma_f32_16x16x32_bf16 v[10:13], v[154:157], v[138:141], v[10:13]
	s_setprio 0
	s_waitcnt vmcnt(0) lgkmcnt(0)
	s_barrier
	ds_read_b128 v[126:129], v221 offset:16384
	ds_read_b128 v[130:133], v221 offset:18432
	ds_read_b128 v[134:137], v221 offset:20480
	ds_read_b128 v[138:141], v221 offset:22528
	ds_read_b128 v[142:145], v223 offset:49152
	ds_read_b128 v[146:149], v223 offset:51200
	ds_read_b128 v[150:153], v223 offset:53248
	ds_read_b128 v[154:157], v223 offset:55296
	s_setprio 1
	s_mov_b32 m0, s93
	v_mfma_f32_16x16x32_bf16 v[62:65], v[176:179], v[158:161], v[62:65]
	global_load_lds_dwordx4 v184, s[88:89]
	s_add_u32 m0, m0, 0x1000
	v_mfma_f32_16x16x32_bf16 v[66:69], v[180:183], v[158:161], v[66:69]
	global_load_lds_dwordx4 v214, s[88:89]
	s_add_u32 m0, m0, 0x1000
	v_mfma_f32_16x16x32_bf16 v[70:73], v[192:195], v[158:161], v[70:73]
	global_load_lds_dwordx4 v215, s[88:89]
	s_add_u32 m0, m0, 0x1000
	v_mfma_f32_16x16x32_bf16 v[2:5], v[210:213], v[158:161], v[2:5]
	global_load_lds_dwordx4 v216, s[88:89]
	s_add_u32 m0, m0, 0x5000
	v_mfma_f32_16x16x32_bf16 v[14:17], v[176:179], v[164:167], v[14:17]
	global_load_lds_dwordx4 v217, s[90:91]
	s_add_u32 m0, m0, 0x1000
	v_mfma_f32_16x16x32_bf16 v[22:25], v[180:183], v[164:167], v[22:25]
	global_load_lds_dwordx4 v218, s[90:91]
	s_add_u32 m0, m0, 0x1000
	v_mfma_f32_16x16x32_bf16 v[30:33], v[192:195], v[164:167], v[30:33]
	global_load_lds_dwordx4 v219, s[90:91]
	s_add_u32 m0, m0, 0x1000
	v_mfma_f32_16x16x32_bf16 v[18:21], v[210:213], v[164:167], v[18:21]
	global_load_lds_dwordx4 v220, s[90:91]
	v_mfma_f32_16x16x32_bf16 v[26:29], v[176:179], v[168:171], v[26:29]
	s_add_u32 s88, s88, 0x80
	v_mfma_f32_16x16x32_bf16 v[34:37], v[180:183], v[168:171], v[34:37]
	s_addc_u32 s89, s89, 0
	v_mfma_f32_16x16x32_bf16 v[58:61], v[192:195], v[168:171], v[58:61]
	s_add_u32 s90, s90, 0x80
	v_mfma_f32_16x16x32_bf16 v[38:41], v[210:213], v[168:171], v[38:41]
	s_addc_u32 s91, s91, 0
	v_mfma_f32_16x16x32_bf16 v[46:49], v[176:179], v[172:175], v[46:49]
	v_mfma_f32_16x16x32_bf16 v[50:53], v[180:183], v[172:175], v[50:53]
	v_mfma_f32_16x16x32_bf16 v[54:57], v[192:195], v[172:175], v[54:57]
	v_mfma_f32_16x16x32_bf16 v[10:13], v[210:213], v[172:175], v[10:13]
	s_setprio 0
	ds_read_b128 v[158:161], v222 offset:16384
	ds_read_b128 v[164:167], v222 offset:18432
	ds_read_b128 v[168:171], v222 offset:20480
	ds_read_b128 v[172:175], v222 offset:22528
	ds_read_b128 v[176:179], v224 offset:49152
	ds_read_b128 v[180:183], v224 offset:51200
	ds_read_b128 v[192:195], v224 offset:53248
	ds_read_b128 v[210:213], v224 offset:55296
	s_setprio 1
	s_waitcnt lgkmcnt(8)
	v_mfma_f32_16x16x32_bf16 v[62:65], v[142:145], v[126:129], v[62:65]
	v_mfma_f32_16x16x32_bf16 v[66:69], v[146:149], v[126:129], v[66:69]
	v_mfma_f32_16x16x32_bf16 v[70:73], v[150:153], v[126:129], v[70:73]
	v_mfma_f32_16x16x32_bf16 v[2:5], v[154:157], v[126:129], v[2:5]
	v_mfma_f32_16x16x32_bf16 v[14:17], v[142:145], v[130:133], v[14:17]
	v_mfma_f32_16x16x32_bf16 v[22:25], v[146:149], v[130:133], v[22:25]
	v_mfma_f32_16x16x32_bf16 v[30:33], v[150:153], v[130:133], v[30:33]
	v_mfma_f32_16x16x32_bf16 v[18:21], v[154:157], v[130:133], v[18:21]
	v_mfma_f32_16x16x32_bf16 v[26:29], v[142:145], v[134:137], v[26:29]
	v_mfma_f32_16x16x32_bf16 v[34:37], v[146:149], v[134:137], v[34:37]
	v_mfma_f32_16x16x32_bf16 v[58:61], v[150:153], v[134:137], v[58:61]
	v_mfma_f32_16x16x32_bf16 v[38:41], v[154:157], v[134:137], v[38:41]
	v_mfma_f32_16x16x32_bf16 v[46:49], v[142:145], v[138:141], v[46:49]
	v_mfma_f32_16x16x32_bf16 v[50:53], v[146:149], v[138:141], v[50:53]
	v_mfma_f32_16x16x32_bf16 v[54:57], v[150:153], v[138:141], v[54:57]
	v_mfma_f32_16x16x32_bf16 v[10:13], v[154:157], v[138:141], v[10:13]
	s_setprio 0
	s_waitcnt vmcnt(0) lgkmcnt(0)
	s_barrier
; #define G_MMA(ks_) __builtin_amdgcn_s_setprio(1); _Pragma("unroll") for (int m = 0; m < 4; ++m) \
;         _Pragma("unroll") for (int n = 0; n < 4; ++n) acc[m][n] = __builtin_amdgcn_mfma_f32_16x16x32_bf16(bfv##ks_[n], af##ks_[m], acc[m][n], 0, 0, 0); __builtin_amdgcn_s_setprio(0);
; template <class Epi>
; DEV void gemm_tile(const bf16_t* __restrict__ A, int lda, const bf16_t* __restrict__ Bt, int ldb, int K, int tm, int tn, char* smem, const Epi& epi) {
;     ...
;     const int nk = K >> 6;
;     G_DMA(0, 0);
;     asm volatile("s_waitcnt vmcnt(0)" ::: "memory");
;     __syncthreads();
; #pragma unroll 4
;     for (int kt = 0; kt < nk; ++kt) {
;         const int cur = kt & 1;
;         if (kt + 1 < nk) G_DMA(cur ^ 1, kt + 1);
;         {
;             G_FRAGS(cur, 0)
;             G_MMA(0)
;             G_FRAGS(cur, 1)
;             G_MMA(1)
;         }
;         asm volatile("s_waitcnt vmcnt(0)" ::: "memory");
;         __syncthreads();
	ds_read_b128 v[126:129], v221
	ds_read_b128 v[130:133], v221 offset:2048
	ds_read_b128 v[134:137], v221 offset:4096
	ds_read_b128 v[138:141], v221 offset:6144
	ds_read_b128 v[142:145], v223 offset:32768
	ds_read_b128 v[146:149], v223 offset:34816
	ds_read_b128 v[150:153], v223 offset:36864
	ds_read_b128 v[154:157], v223 offset:38912
	s_setprio 1
	s_mov_b32 m0, s94
	v_mfma_f32_16x16x32_bf16 v[62:65], v[176:179], v[158:161], v[62:65]
	global_load_lds_dwordx4 v184, s[88:89]
	s_add_u32 m0, m0, 0x1000
	v_mfma_f32_16x16x32_bf16 v[66:69], v[180:183], v[158:161], v[66:69]
	global_load_lds_dwordx4 v214, s[88:89]
	s_add_u32 m0, m0, 0x1000
	v_mfma_f32_16x16x32_bf16 v[70:73], v[192:195], v[158:161], v[70:73]
	global_load_lds_dwordx4 v215, s[88:89]
	s_add_u32 m0, m0, 0x1000
	v_mfma_f32_16x16x32_bf16 v[2:5], v[210:213], v[158:161], v[2:5]
	global_load_lds_dwordx4 v216, s[88:89]
	s_add_u32 m0, m0, 0x5000
	v_mfma_f32_16x16x32_bf16 v[14:17], v[176:179], v[164:167], v[14:17]
	global_load_lds_dwordx4 v217, s[90:91]
	s_add_u32 m0, m0, 0x1000
	v_mfma_f32_16x16x32_bf16 v[22:25], v[180:183], v[164:167], v[22:25]
	global_load_lds_dwordx4 v218, s[90:91]
	s_add_u32 m0, m0, 0x1000
	v_mfma_f32_16x16x32_bf16 v[30:33], v[192:195], v[164:167], v[30:33]
	global_load_lds_dwordx4 v219, s[90:91]
	s_add_u32 m0, m0, 0x1000
	v_mfma_f32_16x16x32_bf16 v[18:21], v[210:213], v[164:167], v[18:21]
	global_load_lds_dwordx4 v220, s[90:91]
	v_mfma_f32_16x16x32_bf16 v[26:29], v[176:179], v[168:171], v[26:29]
	s_add_u32 s88, s88, 0x80
	v_mfma_f32_16x16x32_bf16 v[34:37], v[180:183], v[168:171], v[34:37]
	s_addc_u32 s89, s89, 0
	v_mfma_f32_16x16x32_bf16 v[58:61], v[192:195], v[168:171], v[58:61]
	s_add_u32 s90, s90, 0x80
	v_mfma_f32_16x16x32_bf16 v[38:41], v[210:213], v[168:171], v[38:41]
	s_addc_u32 s91, s91, 0
	v_mfma_f32_16x16x32_bf16 v[46:49], v[176:179], v[172:175], v[46:49]
	v_mfma_f32_16x16x32_bf16 v[50:53], v[180:183], v[172:175], v[50:53]
	v_mfma_f32_16x16x32_bf16 v[54:57], v[192:195], v[172:175], v[54:57]
	v_mfma_f32_16x16x32_bf16 v[10:13], v[210:213], v[172:175], v[10:13]
	s_setprio 0
	s_sub_u32 s92, s92, 1
	s_cmp_lg_u32 s92, 0
	s_cbranch_scc1 .Lgemm_down_loop
	ds_read_b128 v[158:161], v222
	ds_read_b128 v[164:167], v222 offset:2048
	ds_read_b128 v[168:171], v222 offset:4096
	ds_read_b128 v[172:175], v222 offset:6144
	ds_read_b128 v[176:179], v224 offset:32768
	ds_read_b128 v[180:183], v224 offset:34816
	ds_read_b128 v[192:195], v224 offset:36864
	ds_read_b128 v[210:213], v224 offset:38912
	s_setprio 1
	s_waitcnt lgkmcnt(8)
	v_mfma_f32_16x16x32_bf16 v[62:65], v[142:145], v[126:129], v[62:65]
	v_mfma_f32_16x16x32_bf16 v[66:69], v[146:149], v[126:129], v[66:69]
	v_mfma_f32_16x16x32_bf16 v[70:73], v[150:153], v[126:129], v[70:73]
	v_mfma_f32_16x16x32_bf16 v[2:5], v[154:157], v[126:129], v[2:5]
	v_mfma_f32_16x16x32_bf16 v[14:17], v[142:145], v[130:133], v[14:17]
	v_mfma_f32_16x16x32_bf16 v[22:25], v[146:149], v[130:133], v[22:25]
	v_mfma_f32_16x16x32_bf16 v[30:33], v[150:153], v[130:133], v[30:33]
	v_mfma_f32_16x16x32_bf16 v[18:21], v[154:157], v[130:133], v[18:21]
	v_mfma_f32_16x16x32_bf16 v[26:29], v[142:145], v[134:137], v[26:29]
	v_mfma_f32_16x16x32_bf16 v[34:37], v[146:149], v[134:137], v[34:37]
	v_mfma_f32_16x16x32_bf16 v[58:61], v[150:153], v[134:137], v[58:61]
	v_mfma_f32_16x16x32_bf16 v[38:41], v[154:157], v[134:137], v[38:41]
	v_mfma_f32_16x16x32_bf16 v[46:49], v[142:145], v[138:141], v[46:49]
	v_mfma_f32_16x16x32_bf16 v[50:53], v[146:149], v[138:141], v[50:53]
	v_mfma_f32_16x16x32_bf16 v[54:57], v[150:153], v[138:141], v[54:57]
	v_mfma_f32_16x16x32_bf16 v[10:13], v[154:157], v[138:141], v[10:13]
	s_setprio 0
	s_waitcnt vmcnt(0) lgkmcnt(0)
	s_barrier
	ds_read_b128 v[126:129], v221 offset:16384
	ds_read_b128 v[130:133], v221 offset:18432
	ds_read_b128 v[134:137], v221 offset:20480
	ds_read_b128 v[138:141], v221 offset:22528
	ds_read_b128 v[142:145], v223 offset:49152
	ds_read_b128 v[146:149], v223 offset:51200
	ds_read_b128 v[150:153], v223 offset:53248
	ds_read_b128 v[154:157], v223 offset:55296
	s_setprio 1
	v_mfma_f32_16x16x32_bf16 v[62:65], v[176:179], v[158:161], v[62:65]
	v_mfma_f32_16x16x32_bf16 v[66:69], v[180:183], v[158:161], v[66:69]
	v_mfma_f32_16x16x32_bf16 v[70:73], v[192:195], v[158:161], v[70:73]
	v_mfma_f32_16x16x32_bf16 v[2:5], v[210:213], v[158:161], v[2:5]
	v_mfma_f32_16x16x32_bf16 v[14:17], v[176:179], v[164:167], v[14:17]
	v_mfma_f32_16x16x32_bf16 v[22:25], v[180:183], v[164:167], v[22:25]
	v_mfma_f32_16x16x32_bf16 v[30:33], v[192:195], v[164:167], v[30:33]
	v_mfma_f32_16x16x32_bf16 v[18:21], v[210:213], v[164:167], v[18:21]
	v_mfma_f32_16x16x32_bf16 v[26:29], v[176:179], v[168:171], v[26:29]
	v_mfma_f32_16x16x32_bf16 v[34:37], v[180:183], v[168:171], v[34:37]
	v_mfma_f32_16x16x32_bf16 v[58:61], v[192:195], v[168:171], v[58:61]
	v_mfma_f32_16x16x32_bf16 v[38:41], v[210:213], v[168:171], v[38:41]
	v_mfma_f32_16x16x32_bf16 v[46:49], v[176:179], v[172:175], v[46:49]
	v_mfma_f32_16x16x32_bf16 v[50:53], v[180:183], v[172:175], v[50:53]
	v_mfma_f32_16x16x32_bf16 v[54:57], v[192:195], v[172:175], v[54:57]
	v_mfma_f32_16x16x32_bf16 v[10:13], v[210:213], v[172:175], v[10:13]
	s_setprio 0
	ds_read_b128 v[158:161], v222 offset:16384
	ds_read_b128 v[164:167], v222 offset:18432
	ds_read_b128 v[168:171], v222 offset:20480
	ds_read_b128 v[172:175], v222 offset:22528
	ds_read_b128 v[176:179], v224 offset:49152
	ds_read_b128 v[180:183], v224 offset:51200
	ds_read_b128 v[192:195], v224 offset:53248
	ds_read_b128 v[210:213], v224 offset:55296
	s_setprio 1
	s_waitcnt lgkmcnt(8)
	v_mfma_f32_16x16x32_bf16 v[62:65], v[142:145], v[126:129], v[62:65]
	v_mfma_f32_16x16x32_bf16 v[66:69], v[146:149], v[126:129], v[66:69]
	v_mfma_f32_16x16x32_bf16 v[70:73], v[150:153], v[126:129], v[70:73]
	v_mfma_f32_16x16x32_bf16 v[2:5], v[154:157], v[126:129], v[2:5]
	v_mfma_f32_16x16x32_bf16 v[14:17], v[142:145], v[130:133], v[14:17]
	v_mfma_f32_16x16x32_bf16 v[22:25], v[146:149], v[130:133], v[22:25]
	v_mfma_f32_16x16x32_bf16 v[30:33], v[150:153], v[130:133], v[30:33]
	v_mfma_f32_16x16x32_bf16 v[18:21], v[154:157], v[130:133], v[18:21]
	v_mfma_f32_16x16x32_bf16 v[26:29], v[142:145], v[134:137], v[26:29]
	v_mfma_f32_16x16x32_bf16 v[34:37], v[146:149], v[134:137], v[34:37]
	v_mfma_f32_16x16x32_bf16 v[58:61], v[150:153], v[134:137], v[58:61]
	v_mfma_f32_16x16x32_bf16 v[38:41], v[154:157], v[134:137], v[38:41]
	v_mfma_f32_16x16x32_bf16 v[46:49], v[142:145], v[138:141], v[46:49]
	v_mfma_f32_16x16x32_bf16 v[50:53], v[146:149], v[138:141], v[50:53]
	v_mfma_f32_16x16x32_bf16 v[54:57], v[150:153], v[138:141], v[54:57]
	v_mfma_f32_16x16x32_bf16 v[10:13], v[154:157], v[138:141], v[10:13]
	s_setprio 0
	s_waitcnt lgkmcnt(0)
	s_barrier
; #define G_MMA(ks_) __builtin_amdgcn_s_setprio(1); _Pragma("unroll") for (int m = 0; m < 4; ++m) \
;         _Pragma("unroll") for (int n = 0; n < 4; ++n) acc[m][n] = __builtin_amdgcn_mfma_f32_16x16x32_bf16(bfv##ks_[n], af##ks_[m], acc[m][n], 0, 0, 0); __builtin_amdgcn_s_setprio(0);
; template <class Epi>
; DEV void gemm_tile(const bf16_t* __restrict__ A, int lda, const bf16_t* __restrict__ Bt, int ldb, int K, int tm, int tn, char* smem, const Epi& epi) {
;     ...
;     const int nk = K >> 6;
;     G_DMA(0, 0);
;     asm volatile("s_waitcnt vmcnt(0)" ::: "memory");
;     __syncthreads();
; #pragma unroll 4
;     for (int kt = 0; kt < nk; ++kt) {
;         const int cur = kt & 1;
;         if (kt + 1 < nk) G_DMA(cur ^ 1, kt + 1);
;         {
;             G_FRAGS(cur, 0)
;             G_MMA(0)
;             G_FRAGS(cur, 1)
;             G_MMA(1)
;         }
;         asm volatile("s_waitcnt vmcnt(0)" ::: "memory");
;         __syncthreads();
;     }
;     ...
;     float* Ct = (float*)smem;
; #pragma unroll
;     for (int m = 0; m < 4; ++m)
; #pragma unroll
;         for (int n = 0; n < 4; ++n) *(f32x4*)(Ct + (wr * 64 + m * 16 + fr) * CP + wc * 64 + n * 16 + fq * 4) = acc[m][n];
;     __syncthreads();
	s_setprio 1
	v_mfma_f32_16x16x32_bf16 v[62:65], v[176:179], v[158:161], v[62:65]
	v_mfma_f32_16x16x32_bf16 v[66:69], v[180:183], v[158:161], v[66:69]
	v_mfma_f32_16x16x32_bf16 v[70:73], v[192:195], v[158:161], v[70:73]
	v_mfma_f32_16x16x32_bf16 v[2:5], v[210:213], v[158:161], v[2:5]
	v_mfma_f32_16x16x32_bf16 v[14:17], v[176:179], v[164:167], v[14:17]
	v_mfma_f32_16x16x32_bf16 v[22:25], v[180:183], v[164:167], v[22:25]
	v_mfma_f32_16x16x32_bf16 v[30:33], v[192:195], v[164:167], v[30:33]
	v_mfma_f32_16x16x32_bf16 v[18:21], v[210:213], v[164:167], v[18:21]
	v_mfma_f32_16x16x32_bf16 v[26:29], v[176:179], v[168:171], v[26:29]
	v_mfma_f32_16x16x32_bf16 v[34:37], v[180:183], v[168:171], v[34:37]
	v_mfma_f32_16x16x32_bf16 v[58:61], v[192:195], v[168:171], v[58:61]
	v_mfma_f32_16x16x32_bf16 v[38:41], v[210:213], v[168:171], v[38:41]
	v_mfma_f32_16x16x32_bf16 v[46:49], v[176:179], v[172:175], v[46:49]
	v_mfma_f32_16x16x32_bf16 v[50:53], v[180:183], v[172:175], v[50:53]
	v_mfma_f32_16x16x32_bf16 v[54:57], v[192:195], v[172:175], v[54:57]
	v_mfma_f32_16x16x32_bf16 v[10:13], v[210:213], v[172:175], v[10:13]
	s_setprio 0
	v_readlane_b32 s88, v255, 24
	v_readlane_b32 s89, v255, 25
	v_readlane_b32 s90, v255, 26
	v_readlane_b32 s91, v255, 27
	v_readlane_b32 s92, v255, 28
	v_readlane_b32 s93, v255, 29
	v_readlane_b32 s94, v255, 30
	v_readlane_b32 s95, v255, 31
	s_nop 7
	s_nop 1
	s_mul_hi_u32 s39, s39, 0x38e38e39
	s_lshr_b32 s46, s39, 2
	s_mul_i32 s39, s46, 0xfffff700
	s_add_i32 s47, s39, s38
	s_cmpk_lt_i32 s47, 0x800
	s_cselect_b64 s[38:39], -1, 0
	s_mul_i32 s43, s46, 0x6000
	s_and_b64 s[44:45], s[38:39], exec
	v_lshl_or_b32 v7, v8, 6, v7
	s_cselect_b32 s43, s43, 0xc0000
	v_lshl_add_u32 v6, v6, 8, 16
	v_lshlrev_b32_e32 v0, 4, v0
	v_mul_lo_u32 v7, v7, s58
	s_add_u32 s43, s10, s43
	v_add3_u32 v0, v6, v0, v7
	v_mov_b32_e32 v8, v163
	s_addc_u32 s44, s11, 0
	s_lshl_b32 s45, s42, 2
	s_waitcnt vmcnt(0)
	s_barrier
	ds_write_b128 v0, v[62:65]
	ds_write_b128 v0, v[66:69] offset:64
	ds_write_b128 v0, v[70:73] offset:128
	ds_write_b128 v0, v[2:5] offset:192
	ds_write_b128 v0, v[14:17] offset:8448
	ds_write_b128 v0, v[22:25] offset:8512
	ds_write_b128 v0, v[30:33] offset:8576
	ds_write_b128 v0, v[18:21] offset:8640
	ds_write_b128 v0, v[26:29] offset:16896
	ds_write_b128 v0, v[34:37] offset:16960
	ds_write_b128 v0, v[58:61] offset:17024
	ds_write_b128 v0, v[38:41] offset:17088
	ds_write_b128 v0, v[46:49] offset:25344
	ds_write_b128 v0, v[50:53] offset:25408
	ds_write_b128 v0, v[54:57] offset:25472
	ds_write_b128 v0, v[10:13] offset:25536
	s_waitcnt lgkmcnt(0)
	s_barrier
; DEV int tid_() { int t = __builtin_amdgcn_workitem_id_x(); asm volatile("" : "+v"(t)); return t; }
;     DEV void operator()(int tm, int tn, const float* Ct) const {
;         const int row0 = tm * 128, b = row0 / TT, tt0 = row0 - b * TT;
;         const int tid = tid_(), c = (tid & 31) << 2, rb = tid >> 5;
;         const f32x4 g = *(const f32x4*)(mod + (size_t)(tt0 < SEQ ? b : 32) * 6144 + goff + tn * 128 + c);
;         float* x0 = xrow(*p, row0) + tn * 128 + c;
;         const float* xs = from_in ? xrow_in(*p, row0) + tn * 128 + c : x0;
; #pragma unroll
;         for (int it0 = 0; it0 < 16; it0 += 8) {
;             f32x4 xv[8];
; #pragma unroll
;             for (int u = 0; u < 8; ++u) xv[u] = *(const f32x4*)(xs + (size_t)(rb + 8 * (it0 + u)) * D);
; #pragma unroll
;             for (int u = 0; u < 8; ++u) { const int r = rb + 8 * (it0 + u); *(f32x4*)(x0 + (size_t)r * D) = xv[u] + g * *(const f32x4*)(Ct + r * CP + c); }
;         }
	s_add_u32 s42, s43, s45
	v_lshlrev_b32_e32 v0, 4, v8
	s_addc_u32 s43, s44, 0
	v_and_b32_e32 v0, 0x1f0, v0
	v_lshl_add_u64 v[2:3], s[42:43], 0, v[0:1]
	s_movk_i32 s42, 0x5000
	v_add_co_u32_e32 v2, vcc, s42, v2
	s_add_i32 s42, s47, 0xfffff800
	s_ashr_i32 s43, s47, 31
	s_and_b64 s[38:39], s[38:39], exec
	v_readlane_b32 s48, v251, 1
	v_readlane_b32 s51, v251, 4
	v_readlane_b32 s38, v251, 36
	s_cselect_b32 s44, 23, 20
	v_readlane_b32 s49, v251, 2
	v_readlane_b32 s50, v251, 3
	s_cselect_b32 s48, s51, s38
	v_readlane_b32 s38, v251, 35
	s_cselect_b32 s49, s50, s38
	s_cselect_b32 s39, s43, 0
	s_cselect_b32 s38, s47, s42
	s_lshl_b32 s42, s46, s44
	s_add_u32 s42, s49, s42
	s_addc_u32 s43, s48, 0
	s_lshl_b64 s[38:39], s[38:39], 12
	s_add_u32 s38, s42, s38
	s_addc_u32 s39, s43, s39
	s_add_u32 s38, s38, s45
	v_ashrrev_i32_e32 v40, 5, v8
	s_addc_u32 s39, s39, 0
	v_ashrrev_i32_e32 v41, 31, v40
	v_lshl_add_u64 v[6:7], s[38:39], 0, v[0:1]
	v_lshlrev_b64 v[8:9], 12, v[40:41]
	v_addc_co_u32_e32 v3, vcc, 0, v3, vcc
	v_lshl_add_u64 v[6:7], v[6:7], 0, v[8:9]
	global_load_dwordx4 v[2:5], v[2:3], off
	s_mov_b32 s38, 0x8000
	global_load_dwordx4 v[8:11], v[6:7], off
	v_add_co_u32_e32 v44, vcc, s38, v6
	s_mov_b32 s38, 0x10000
	s_nop 0
	v_addc_co_u32_e32 v45, vcc, 0, v7, vcc
	global_load_dwordx4 v[12:15], v[44:45], off
	v_add_co_u32_e32 v46, vcc, s38, v6
	s_mov_b32 s38, 0x18000
	s_nop 0
	v_addc_co_u32_e32 v47, vcc, 0, v7, vcc
	global_load_dwordx4 v[16:19], v[46:47], off
	v_add_co_u32_e32 v48, vcc, s38, v6
	s_mov_b32 s38, 0x20000
	s_nop 0
	v_addc_co_u32_e32 v49, vcc, 0, v7, vcc
	global_load_dwordx4 v[20:23], v[48:49], off
	v_add_co_u32_e32 v50, vcc, s38, v6
	s_mov_b32 s38, 0x28000
	s_nop 0
	v_addc_co_u32_e32 v51, vcc, 0, v7, vcc
	global_load_dwordx4 v[24:27], v[50:51], off
	v_add_co_u32_e32 v52, vcc, s38, v6
	s_mov_b32 s38, 0x30000
	s_nop 0
	v_addc_co_u32_e32 v53, vcc, 0, v7, vcc
	global_load_dwordx4 v[28:31], v[52:53], off
	v_add_co_u32_e32 v54, vcc, s38, v6
	s_mov_b32 s38, 0x38000
	s_nop 0
	v_addc_co_u32_e32 v55, vcc, 0, v7, vcc
	global_load_dwordx4 v[32:35], v[54:55], off
	v_add_co_u32_e32 v56, vcc, s38, v6
	v_mul_lo_u32 v40, v40, s58
	s_nop 0
	v_addc_co_u32_e32 v57, vcc, 0, v7, vcc
	global_load_dwordx4 v[36:39], v[56:57], off
	v_add3_u32 v0, 16, v0, v40
	ds_read_b128 v[40:43], v0
	s_mov_b32 s38, 0x40000
	s_waitcnt vmcnt(7) lgkmcnt(0)
	v_pk_fma_f32 v[10:11], v[4:5], v[42:43], v[10:11]
	v_pk_fma_f32 v[8:9], v[2:3], v[40:41], v[8:9]
	global_store_dwordx4 v[6:7], v[8:11], off
	ds_read_b128 v[8:11], v0 offset:4224
	s_waitcnt vmcnt(7) lgkmcnt(0)
	v_pk_fma_f32 v[10:11], v[4:5], v[10:11], v[14:15]
	v_pk_fma_f32 v[8:9], v[2:3], v[8:9], v[12:13]
	global_store_dwordx4 v[44:45], v[8:11], off
	ds_read_b128 v[8:11], v0 offset:8448
	s_waitcnt vmcnt(7) lgkmcnt(0)
	v_pk_fma_f32 v[10:11], v[4:5], v[10:11], v[18:19]
	v_pk_fma_f32 v[8:9], v[2:3], v[8:9], v[16:17]
	global_store_dwordx4 v[46:47], v[8:11], off
	ds_read_b128 v[8:11], v0 offset:12672
	s_waitcnt vmcnt(7) lgkmcnt(0)
	v_pk_fma_f32 v[10:11], v[4:5], v[10:11], v[22:23]
	v_pk_fma_f32 v[8:9], v[2:3], v[8:9], v[20:21]
	global_store_dwordx4 v[48:49], v[8:11], off
	ds_read_b128 v[8:11], v0 offset:16896
	s_waitcnt vmcnt(7) lgkmcnt(0)
	v_pk_fma_f32 v[10:11], v[4:5], v[10:11], v[26:27]
	v_pk_fma_f32 v[8:9], v[2:3], v[8:9], v[24:25]
	global_store_dwordx4 v[50:51], v[8:11], off
	ds_read_b128 v[8:11], v0 offset:21120
	ds_read_b128 v[48:51], v0 offset:33792
	s_waitcnt vmcnt(7) lgkmcnt(1)
	v_pk_fma_f32 v[10:11], v[4:5], v[10:11], v[30:31]
	v_pk_fma_f32 v[8:9], v[2:3], v[8:9], v[28:29]
	global_store_dwordx4 v[52:53], v[8:11], off
	ds_read_b128 v[8:11], v0 offset:25344
	v_add_co_u32_e32 v52, vcc, s38, v6
	s_mov_b32 s38, 0x48000
	s_nop 0
	v_addc_co_u32_e32 v53, vcc, 0, v7, vcc
	s_waitcnt vmcnt(7) lgkmcnt(0)
	v_pk_fma_f32 v[10:11], v[4:5], v[10:11], v[34:35]
	v_pk_fma_f32 v[8:9], v[2:3], v[8:9], v[32:33]
	global_store_dwordx4 v[54:55], v[8:11], off
	ds_read_b128 v[8:11], v0 offset:29568
	v_add_co_u32_e32 v54, vcc, s38, v6
	s_mov_b32 s38, 0x50000
	s_nop 0
	v_addc_co_u32_e32 v55, vcc, 0, v7, vcc
	s_waitcnt vmcnt(7) lgkmcnt(0)
	v_pk_fma_f32 v[10:11], v[4:5], v[10:11], v[38:39]
	v_pk_fma_f32 v[8:9], v[2:3], v[8:9], v[36:37]
	global_load_dwordx4 v[36:39], v[52:53], off
	global_load_dwordx4 v[40:43], v[54:55], off
	s_nop 0
	global_store_dwordx4 v[56:57], v[8:11], off
	v_add_co_u32_e32 v56, vcc, s38, v6
	s_mov_b32 s38, 0x58000
	s_nop 0
	v_addc_co_u32_e32 v57, vcc, 0, v7, vcc
	global_load_dwordx4 v[44:47], v[56:57], off
	v_add_co_u32_e32 v34, vcc, s38, v6
	s_mov_b32 s38, 0x60000
	s_nop 0
	v_addc_co_u32_e32 v35, vcc, 0, v7, vcc
	global_load_dwordx4 v[22:25], v[34:35], off
	v_add_co_u32_e32 v32, vcc, s38, v6
	s_mov_b32 s38, 0x68000
	s_nop 0
	v_addc_co_u32_e32 v33, vcc, 0, v7, vcc
	global_load_dwordx4 v[18:21], v[32:33], off
	v_add_co_u32_e32 v30, vcc, s38, v6
	s_mov_b32 s38, 0x70000
	s_nop 0
	v_addc_co_u32_e32 v31, vcc, 0, v7, vcc
	global_load_dwordx4 v[14:17], v[30:31], off
	v_add_co_u32_e32 v28, vcc, s38, v6
	s_mov_b32 s38, 0x78000
	s_nop 0
	v_addc_co_u32_e32 v29, vcc, 0, v7, vcc
	global_load_dwordx4 v[10:13], v[28:29], off
	v_add_co_u32_e32 v26, vcc, s38, v6
	s_waitcnt vmcnt(7)
	v_pk_fma_f32 v[38:39], v[4:5], v[50:51], v[38:39]
	v_addc_co_u32_e32 v27, vcc, 0, v7, vcc
	global_load_dwordx4 v[6:9], v[26:27], off
	v_pk_fma_f32 v[36:37], v[2:3], v[48:49], v[36:37]
	global_store_dwordx4 v[52:53], v[36:39], off
	ds_read_b128 v[36:39], v0 offset:38016
	s_waitcnt vmcnt(8) lgkmcnt(0)
	v_pk_fma_f32 v[38:39], v[4:5], v[38:39], v[42:43]
	v_pk_fma_f32 v[36:37], v[2:3], v[36:37], v[40:41]
	global_store_dwordx4 v[54:55], v[36:39], off
	ds_read_b128 v[36:39], v0 offset:42240
	s_waitcnt vmcnt(7) lgkmcnt(0)
	v_pk_fma_f32 v[38:39], v[4:5], v[38:39], v[46:47]
	v_pk_fma_f32 v[36:37], v[2:3], v[36:37], v[44:45]
	global_store_dwordx4 v[56:57], v[36:39], off
	ds_read_b128 v[36:39], v0 offset:46464
	s_waitcnt vmcnt(7) lgkmcnt(0)
	v_pk_fma_f32 v[24:25], v[4:5], v[38:39], v[24:25]
	v_pk_fma_f32 v[22:23], v[2:3], v[36:37], v[22:23]
	global_store_dwordx4 v[34:35], v[22:25], off
	ds_read_b128 v[22:25], v0 offset:50688
	s_waitcnt vmcnt(7) lgkmcnt(0)
	v_pk_fma_f32 v[20:21], v[4:5], v[24:25], v[20:21]
	v_pk_fma_f32 v[18:19], v[2:3], v[22:23], v[18:19]
	global_store_dwordx4 v[32:33], v[18:21], off
	ds_read_b128 v[18:21], v0 offset:54912
	s_waitcnt vmcnt(7) lgkmcnt(0)
	v_pk_fma_f32 v[16:17], v[4:5], v[20:21], v[16:17]
	v_pk_fma_f32 v[14:15], v[2:3], v[18:19], v[14:15]
	global_store_dwordx4 v[30:31], v[14:17], off
	ds_read_b128 v[14:17], v0 offset:59136
	s_waitcnt vmcnt(7) lgkmcnt(0)
	v_pk_fma_f32 v[12:13], v[4:5], v[16:17], v[12:13]
	v_pk_fma_f32 v[10:11], v[2:3], v[14:15], v[10:11]
	global_store_dwordx4 v[28:29], v[10:13], off
	ds_read_b128 v[10:13], v0 offset:63360
	s_waitcnt vmcnt(7) lgkmcnt(0)
	v_pk_fma_f32 v[4:5], v[4:5], v[12:13], v[8:9]
	v_pk_fma_f32 v[2:3], v[2:3], v[10:11], v[6:7]
	global_store_dwordx4 v[26:27], v[2:5], off
	s_barrier
	s_branch .LBB0_178

; DEV int tid_() { int t = __builtin_amdgcn_workitem_id_x(); asm volatile("" : "+v"(t)); return t; }
; DEV void scan_item(const bf16_t* SC, float* Y, int bl, int h, int dir, const float* k_a, char* smem) {
;     const int tid = tid_(), lane = tid & 63, w = tid >> 6, ch = lane, sq = w;
;     float* stg = (float*)smem;
;     float* yb = stg + 2 * 16 * 6 * 64;
;     const float ka = k_a[h * 64 + ch];
;     unsigned short pre[4][6];
;     float S[16];
; #pragma unroll
;     for (int j = 0; j < 16; ++j) S[j] = 0.f;
; DEV void phase_mix(const Params& p, int l, int c, int phase_idx, char* smem, int rmask, int* s_item) {
;     ...
;         const int bl = it >> 3, h = (it >> 1) & 3, dir = it & 1;
;         __builtin_amdgcn_s_setprio(3);
;         scan_item((const bf16_t*)(scr + SO_SC), (float*)(scr + SO_Y), bl, h, dir, p.in[22] + l * 256, smem);
.LBB0_203:
	s_and_b32 s40, s36, 1
	s_ashr_i32 s3, s36, 3
	s_bfe_u32 s2, s36, 0x20001
	s_setprio 0
	v_mov_b32_e32 v10, v163
	s_cmp_eq_u32 s40, 0
	s_cselect_b64 s[38:39], -1, 0
	v_ashrrev_i32_e32 v40, 6, v10
	s_lshl_b32 s41, s2, 10
	v_readlane_b32 s42, v251, 41
	v_cmp_gt_i32_e32 vcc, s59, v40
	s_add_u32 s42, s42, s41
	s_movk_i32 s41, 0xfc
	s_waitcnt vmcnt(11)
	v_cndmask_b32_e32 v0, v196, v197, vcc
	v_cmp_gt_i32_e32 vcc, s41, v40
	s_movk_i32 s41, 0xf8
	v_add_u32_e32 v11, 4, v40
	v_cndmask_b32_e32 v4, v196, v197, vcc
	v_cmp_gt_i32_e32 vcc, s41, v40
	v_add_u32_e32 v2, v0, v40
	v_sub_u32_e32 v42, 0x8ff, v40
	v_add_u32_e32 v4, v4, v11
	v_sub_u32_e32 v5, 0x8fb, v40
	s_waitcnt vmcnt(6)
	v_add_u32_e32 v30, 8, v40
	v_cndmask_b32_e32 v8, v196, v197, vcc
	s_mul_i32 s37, s3, 0x900
	v_cndmask_b32_e64 v2, v42, v2, s[38:39]
	v_cndmask_b32_e64 v4, v5, v4, s[38:39]
	v_add_u32_e32 v8, v8, v30
	v_sub_u32_e32 v9, 0x8f7, v40
	v_and_b32_e32 v37, 63, v10
	v_readlane_b32 s43, v251, 42
	v_add_u32_e32 v2, s37, v2
	v_add_u32_e32 v4, s37, v4
	v_cndmask_b32_e64 v8, v9, v8, s[38:39]
	s_addc_u32 s43, s43, 0
	v_lshlrev_b32_e32 v0, 1, v37
	v_ashrrev_i32_e32 v3, 31, v2
	v_ashrrev_i32_e32 v5, 31, v4
	v_add_u32_e32 v8, s37, v8
	v_lshl_add_u64 v[34:35], s[42:43], 0, v[0:1]
	v_lshlrev_b64 v[2:3], 12, v[2:3]
	v_lshlrev_b64 v[4:5], 12, v[4:5]
	v_ashrrev_i32_e32 v9, 31, v8
	s_movk_i32 s41, 0xf4
	v_lshl_add_u64 v[2:3], v[34:35], 0, v[2:3]
	s_lshl_b32 s94, s40, 7
	v_lshl_add_u64 v[4:5], v[34:35], 0, v[4:5]
	v_lshlrev_b64 v[8:9], 12, v[8:9]
	v_cmp_gt_i32_e32 vcc, s41, v40
	global_load_ushort v12, v[2:3], off
	global_load_ushort v13, v[2:3], off offset:128
	global_load_ushort v14, v[2:3], off offset:256
	global_load_ushort v15, v[2:3], off offset:384
	global_load_ushort v16, v[4:5], off
	global_load_ushort v17, v[4:5], off offset:128
	v_lshl_add_u64 v[6:7], v[4:5], 0, s[94:95]
	v_lshl_add_u64 v[8:9], v[34:35], 0, v[8:9]
	global_load_ushort v31, v[4:5], off offset:256
	global_load_ushort v32, v[4:5], off offset:384
	global_load_ushort v33, v[6:7], off offset:512
	global_load_ushort v38, v[6:7], off offset:768
	global_load_ushort v39, v[8:9], off
	global_load_ushort v43, v[8:9], off offset:128
	global_load_ushort v44, v[8:9], off offset:256
	global_load_ushort v45, v[8:9], off offset:384
	v_add_u32_e32 v46, 12, v40
	v_cndmask_b32_e32 v4, v196, v197, vcc
	v_add_u32_e32 v4, v4, v46
	v_sub_u32_e32 v5, 0x8f3, v40
	v_cndmask_b32_e64 v4, v5, v4, s[38:39]
	v_add_u32_e32 v4, s37, v4
	v_ashrrev_i32_e32 v5, 31, v4
	v_lshlrev_b64 v[4:5], 12, v[4:5]
	v_lshl_add_u64 v[4:5], v[34:35], 0, v[4:5]
	global_load_ushort v47, v[4:5], off
	global_load_ushort v48, v[4:5], off offset:128
	global_load_ushort v49, v[4:5], off offset:256
	global_load_ushort v50, v[4:5], off offset:384
	v_lshl_add_u64 v[6:7], v[8:9], 0, s[94:95]
	v_lshl_add_u64 v[4:5], v[4:5], 0, s[94:95]
	v_lshl_add_u64 v[2:3], v[2:3], 0, s[94:95]
	global_load_ushort v8, v[6:7], off offset:512
	global_load_ushort v9, v[4:5], off offset:512
	s_nop 0
	global_load_ushort v4, v[4:5], off offset:768
	s_nop 0
	global_load_ushort v5, v[6:7], off offset:768
	s_nop 0
	global_load_ushort v6, v[2:3], off offset:512
	s_nop 0
	global_load_ushort v2, v[2:3], off offset:768
	v_lshlrev_b32_e32 v3, 2, v37
	v_lshl_or_b32 v7, s2, 8, v3
	global_load_dword v41, v7, s[0:1]
	v_add_u32_e32 v36, 16, v3
	s_movk_i32 s41, 0x600
	s_lshl_b32 s45, s40, 6
	v_readlane_b32 s4, v251, 43
	s_mul_i32 s40, s40, 0x12000
	v_readlane_b32 s5, v251, 44
	s_mul_hi_i32 s3, s3, 0x900
	s_add_u32 s40, s37, s40
	s_mov_b32 s44, 0
	v_mov_b32_e32 v54, 0
	v_mov_b32_e32 v51, 0
	v_mov_b32_e32 v52, 0
	v_mov_b32_e32 v53, 0
	v_mov_b32_e32 v55, 0
	v_mov_b32_e32 v56, 0
	v_mov_b32_e32 v57, 0
	v_mov_b32_e32 v58, 0
	v_mov_b32_e32 v59, 0
	v_mov_b32_e32 v60, 0
	v_mov_b32_e32 v61, 0
	v_mov_b32_e32 v62, 0
	v_mov_b32_e32 v63, 0
	v_mov_b32_e32 v64, 0
	v_mov_b32_e32 v65, 0
	s_waitcnt vmcnt(24)
; DEV void scan_item(const bf16_t* SC, float* Y, int bl, int h, int dir, const float* k_a, char* smem) {
;     ...
;     SC_GL(0); SC_ST(0);
;     __syncthreads();
;     constexpr int NCH = TT / 16;
;     const int vrow = w * 16 + (lane & 15);
	v_lshlrev_b32_e32 v7, 16, v12
	s_waitcnt vmcnt(23)
	v_perm_b32 v18, v13, v12, s30
	v_lshlrev_b32_e32 v12, 16, v13
	s_waitcnt vmcnt(21)
	v_perm_b32 v19, v15, v14, s30
	v_lshlrev_b32_e32 v13, 16, v14
	v_lshlrev_b32_e32 v14, 16, v15
	s_waitcnt vmcnt(13)
	v_perm_b32 v24, v43, v39, s30
	v_perm_b32 v23, v38, v33, s30
	s_waitcnt vmcnt(11)
	v_perm_b32 v25, v45, v44, s30
	v_perm_b32 v22, v32, v31, s30
	v_perm_b32 v21, v17, v16, s30
	s_waitcnt vmcnt(9)
	v_perm_b32 v27, v48, v47, s30
	s_waitcnt vmcnt(7)
	v_perm_b32 v28, v50, v49, s30
	s_waitcnt vmcnt(4)
	v_perm_b32 v29, v4, v9, s30
	s_waitcnt vmcnt(2)
	v_lshlrev_b32_e32 v3, 16, v6
	s_waitcnt vmcnt(1)
	v_perm_b32 v20, v2, v6, s30
	v_lshlrev_b32_e32 v6, 16, v2
	v_mul_f32_e32 v2, 0xbfb8aa3b, v3
	v_exp_f32_e32 v15, v2
	v_mad_u64_u32 v[2:3], s[42:43], v40, s41, v[36:37]
	v_xor_b32_e32 v3, 0x80000000, v14
	ds_write2st64_b32 v2, v3, v15 offset1:1
	v_mul_f32_e32 v3, v14, v6
	v_add_f32_e32 v6, -1.0, v6
	s_waitcnt vmcnt(0)
	v_fma_f32 v6, v41, v6, 1.0
	v_mul_f32_e32 v6, v6, v13
	ds_write2st64_b32 v2, v3, v6 offset0:2 offset1:3
	ds_write2st64_b32 v2, v7, v12 offset0:4 offset1:5
	v_lshlrev_b32_e32 v12, 16, v33
	v_mul_f32_e32 v12, 0xbfb8aa3b, v12
	v_exp_f32_e32 v12, v12
	v_lshlrev_b32_e32 v13, 16, v32
	v_perm_b32 v26, v5, v8, s30
	v_lshlrev_b32_e32 v14, 16, v38
	v_xor_b32_e32 v15, 0x80000000, v13
	v_lshlrev_b32_e32 v8, 16, v8
	ds_write2st64_b32 v2, v15, v12 offset0:24 offset1:25
	v_mul_f32_e32 v12, v13, v14
	v_add_f32_e32 v13, -1.0, v14
	v_mul_f32_e32 v8, 0xbfb8aa3b, v8
	v_lshlrev_b32_e32 v7, 16, v31
	v_fma_f32 v13, v41, v13, 1.0
	v_exp_f32_e32 v8, v8
	v_mul_f32_e32 v7, v13, v7
	v_lshlrev_b32_e32 v3, 16, v16
	v_lshlrev_b32_e32 v6, 16, v17
	ds_write2st64_b32 v2, v12, v7 offset0:26 offset1:27
	ds_write2st64_b32 v2, v3, v6 offset0:28 offset1:29
	v_lshlrev_b32_e32 v12, 16, v45
	v_lshlrev_b32_e32 v5, 16, v5
	v_xor_b32_e32 v13, 0x80000000, v12
	ds_write2st64_b32 v2, v13, v8 offset0:48 offset1:49
	v_mul_f32_e32 v8, v12, v5
	v_add_f32_e32 v5, -1.0, v5
	v_lshlrev_b32_e32 v7, 16, v44
	v_fma_f32 v5, v41, v5, 1.0
	v_mul_f32_e32 v5, v5, v7
	v_lshlrev_b32_e32 v7, 16, v9
	v_mul_f32_e32 v7, 0xbfb8aa3b, v7
	v_exp_f32_e32 v7, v7
	v_lshlrev_b32_e32 v3, 16, v39
	v_lshlrev_b32_e32 v6, 16, v43
	ds_write2st64_b32 v2, v8, v5 offset0:50 offset1:51
	ds_write2st64_b32 v2, v3, v6 offset0:52 offset1:53
	v_lshlrev_b32_e32 v8, 16, v50
	v_lshlrev_b32_e32 v4, 16, v4
	v_xor_b32_e32 v9, 0x80000000, v8
	ds_write2st64_b32 v2, v9, v7 offset0:72 offset1:73
	v_mul_f32_e32 v7, v8, v4
	v_add_f32_e32 v4, -1.0, v4
	v_lshlrev_b32_e32 v6, 16, v49
	v_fma_f32 v4, v41, v4, 1.0
	v_mul_f32_e32 v4, v4, v6
	v_lshlrev_b32_e32 v3, 16, v47
	v_lshlrev_b32_e32 v5, 16, v48
	ds_write2st64_b32 v2, v7, v4 offset0:74 offset1:75
	ds_write2st64_b32 v2, v3, v5 offset0:76 offset1:77
	v_and_b32_e32 v2, 15, v10
	v_lshl_or_b32 v43, v40, 4, v2
	v_lshlrev_b32_e32 v2, 4, v10
	v_and_b32_e32 v2, 0x300, v2
	v_lshlrev_b32_e32 v3, 2, v43
	v_add3_u32 v44, 16, v2, v3
	v_lshl_add_u64 v[2:3], s[4:5], 0, v[0:1]
	s_addc_u32 s41, s3, 0
	s_lshl_b32 s94, s2, 7
	v_lshl_add_u64 v[38:39], v[2:3], 0, s[94:95]
	v_lshlrev_b32_e32 v0, 10, v40
	v_lshlrev_b32_e32 v2, 10, v11
	v_lshlrev_b32_e32 v3, 10, v30
	v_lshlrev_b32_e32 v4, 10, v46
	v_mov_b32_e32 v50, 0
	s_lshl_b32 s94, s45, 1
	v_add_u32_e32 v0, v36, v0
	v_add_u32_e32 v45, v36, v2
	v_add_u32_e32 v46, v36, v3
	v_add_u32_e32 v47, v36, v4
	s_mov_b32 s45, 0
	s_waitcnt lgkmcnt(0)
	s_barrier
	s_branch .LBB0_205

; DEV int tid_() { int t = __builtin_amdgcn_workitem_id_x(); asm volatile("" : "+v"(t)); return t; }
; template <class Epi>
; DEV void gemm_tile(const bf16_t* __restrict__ A, int lda, const bf16_t* __restrict__ Bt, int ldb, int K, int tm, int tn, char* smem, const Epi& epi) {
;     const int tid = tid_(), lane = tid & 63, wid = tid >> 6, wr = wid >> 1, wc = wid & 1, fr = lane & 15, fq = lane >> 4;
;     bf16_t* As = (bf16_t*)smem;
;     bf16_t* Bs = As + 2 * 128 * 64;
;     const int lrow = tid >> 3, lcc = (tid & 7) * 8, lsw = (((tid & 7) ^ (lrow & 7)) * 8);
;     const bf16_t* Ag = A + (size_t)(tm * 128 + lrow) * lda + lcc;
;     const bf16_t* Bg = Bt + (size_t)(tn * 128 + lrow) * ldb + lcc;
;     f32x4 acc[4][4];
; #pragma unroll
;     for (int m = 0; m < 4; ++m)
; #pragma unroll
;         for (int n = 0; n < 4; ++n) acc[m][n] = (f32x4){0.f, 0.f, 0.f, 0.f};
;     const int gsw = (((tid & 7) ^ (lrow & 7)) * 8);
;     const bf16_t* Ad = A + (size_t)(tm * 128 + lrow) * lda + gsw;
;     const bf16_t* Bd = Bt + (size_t)(tn * 128 + lrow) * ldb + gsw;
;     char* Asb = (char*)As; char* Bsb = (char*)Bs;
;     ...
;     const int nk = K >> 6;
;     G_DMA(0, 0);
;     asm volatile("s_waitcnt vmcnt(0)" ::: "memory");
;     __syncthreads();
; #pragma unroll 4
;     for (int kt = 0; kt < nk; ++kt) {
;         const int cur = kt & 1;
;         if (kt + 1 < nk) G_DMA(cur ^ 1, kt + 1);
.LBB0_683:
	v_readlane_b32 s0, v253, 32
	s_add_i32 s48, s2, s0
	v_mov_b32_e32 v12, v163
	s_lshl_b32 s51, s48, 7
	v_ashrrev_i32_e32 v14, 3, v12
	s_lshl_b32 s50, s62, 7
	v_add_u32_e32 v2, s51, v14
	v_add_u32_e32 v4, s50, v14
	v_ashrrev_i32_e32 v3, 31, v2
	v_ashrrev_i32_e32 v5, 31, v4
	s_waitcnt vmcnt(10)
	v_xor_b32_e32 v0, v14, v12
	v_lshlrev_b64 v[2:3], 11, v[2:3]
	v_lshlrev_b64 v[4:5], 11, v[4:5]
	v_lshlrev_b32_e32 v0, 4, v0
	v_lshl_add_u64 v[6:7], s[38:39], 0, v[2:3]
	v_lshl_add_u64 v[8:9], s[40:41], 0, v[4:5]
	v_and_b32_e32 v0, 0x70, v0
	v_lshl_add_u64 v[6:7], v[6:7], 0, v[0:1]
	v_lshl_add_u64 v[8:9], v[8:9], 0, v[0:1]
	v_lshlrev_b32_e32 v0, 4, v12
	v_add_u32_e32 v0, 16, v0
	v_add_u32_e32 v76, 0x8000, v0
	v_readfirstlane_b32 s0, v0
	s_mov_b32 m0, s0
	v_readfirstlane_b32 s0, v76
	v_add_u32_e32 v77, 0x1000, v0
	global_load_lds_dwordx4 v[6:7], off
	s_mov_b32 m0, s0
	s_mov_b64 s[2:3], 0x10000
	v_readfirstlane_b32 s0, v77
	v_add_u32_e32 v78, 0x9000, v0
	global_load_lds_dwordx4 v[8:9], off
	v_lshl_add_u64 v[10:11], v[6:7], 0, s[2:3]
	s_mov_b32 m0, s0
	v_readfirstlane_b32 s0, v78
	v_add_u32_e32 v79, 0x2000, v0
	global_load_lds_dwordx4 v[10:11], off
	v_lshl_add_u64 v[10:11], v[8:9], 0, s[2:3]
	s_mov_b32 m0, s0
	s_mov_b64 s[2:3], 0x20000
	v_readfirstlane_b32 s0, v79
	v_add_u32_e32 v80, 0xa000, v0
	global_load_lds_dwordx4 v[10:11], off
	v_lshl_add_u64 v[10:11], v[6:7], 0, s[2:3]
	s_mov_b32 m0, s0
	v_readfirstlane_b32 s0, v80
	v_add_u32_e32 v81, 0x3000, v0
	global_load_lds_dwordx4 v[10:11], off
	v_lshl_add_u64 v[10:11], v[8:9], 0, s[2:3]
	s_mov_b32 m0, s0
	s_mov_b64 s[2:3], 0x30000
	v_readfirstlane_b32 s0, v81
	v_add_u32_e32 v82, 0xb000, v0
	global_load_lds_dwordx4 v[10:11], off
	v_lshl_add_u64 v[6:7], v[6:7], 0, s[2:3]
	s_mov_b32 m0, s0
	v_readfirstlane_b32 s0, v82
	global_load_lds_dwordx4 v[6:7], off
	v_lshl_add_u64 v[6:7], v[8:9], 0, s[2:3]
	s_mov_b32 m0, s0
	v_lshrrev_b32_e32 v13, 4, v12
	global_load_lds_dwordx4 v[6:7], off
	v_and_b32_e32 v75, 15, v12
	v_ashrrev_i32_e32 v84, 7, v12
	v_bfe_u32 v83, v12, 4, 2
	v_and_b32_e32 v8, 7, v12
	v_lshlrev_b32_e32 v6, 13, v84
	v_lshlrev_b32_e32 v7, 7, v75
	v_bitop3_b32 v9, v13, v8, 3 bitop3:0x6c
	v_bitop3_b32 v8, v83, v8, 4 bitop3:0x36
	v_add3_u32 v6, 16, v6, v7
	v_lshlrev_b32_e32 v9, 4, v9
	v_lshlrev_b32_e32 v8, 4, v8
	v_add_u32_e32 v85, v6, v9
	v_add_u32_e32 v87, v6, v8
	v_bitop3_b32 v6, v14, 7, v12 bitop3:0x48
	v_bfe_u32 v74, v12, 6, 1
	v_lshlrev_b32_e32 v6, 4, v6
	s_waitcnt vmcnt(0)
	v_lshlrev_b32_e32 v10, 13, v74
	v_or_b32_e32 v2, v2, v6
	v_add3_u32 v7, 16, v10, v7
	v_or_b32_e32 v4, v4, v6
	v_lshl_add_u64 v[68:69], s[44:45], 0, v[2:3]
	v_mov_b32_e32 v2, 0
	v_add_u32_e32 v86, v7, v9
	v_add_u32_e32 v88, v7, v8
	v_lshl_add_u64 v[66:67], s[42:43], 0, v[4:5]
	s_mov_b64 s[0:1], 0
	v_mov_b32_e32 v3, v2
	v_mov_b32_e32 v4, v2
	v_mov_b32_e32 v5, v2
	v_mov_b32_e32 v6, v2
	v_mov_b32_e32 v7, v2
	v_mov_b32_e32 v8, v2
	v_mov_b32_e32 v9, v2
	v_mov_b32_e32 v10, v2
	v_mov_b32_e32 v11, v2
	v_mov_b32_e32 v12, v2
	v_mov_b32_e32 v13, v2
	v_mov_b32_e32 v14, v2
	v_mov_b32_e32 v15, v2
	v_mov_b32_e32 v16, v2
	v_mov_b32_e32 v17, v2
	s_waitcnt vmcnt(0)
	v_mov_b32_e32 v18, v2
	v_mov_b32_e32 v19, v2
	v_mov_b32_e32 v20, v2
	v_mov_b32_e32 v21, v2
	v_mov_b32_e32 v22, v2
	v_mov_b32_e32 v23, v2
	v_mov_b32_e32 v24, v2
	v_mov_b32_e32 v25, v2
	s_waitcnt vmcnt(0)
	v_mov_b32_e32 v26, v2
	v_mov_b32_e32 v27, v2
	v_mov_b32_e32 v28, v2
	v_mov_b32_e32 v29, v2
	v_mov_b32_e32 v30, v2
	v_mov_b32_e32 v31, v2
	v_mov_b32_e32 v32, v2
	v_mov_b32_e32 v33, v2
	v_mov_b32_e32 v34, v2
	v_mov_b32_e32 v35, v2
	v_mov_b32_e32 v36, v2
	v_mov_b32_e32 v37, v2
	v_mov_b32_e32 v38, v2
	v_mov_b32_e32 v39, v2
	v_mov_b32_e32 v40, v2
	v_mov_b32_e32 v41, v2
	v_mov_b32_e32 v42, v2
	v_mov_b32_e32 v43, v2
	v_mov_b32_e32 v44, v2
	v_mov_b32_e32 v45, v2
	v_mov_b32_e32 v46, v2
	v_mov_b32_e32 v47, v2
	v_mov_b32_e32 v48, v2
	v_mov_b32_e32 v49, v2
	v_mov_b32_e32 v50, v2
	v_mov_b32_e32 v51, v2
	v_mov_b32_e32 v52, v2
	v_mov_b32_e32 v53, v2
	v_mov_b32_e32 v54, v2
	v_mov_b32_e32 v55, v2
	v_mov_b32_e32 v56, v2
	v_mov_b32_e32 v57, v2
	v_mov_b32_e32 v58, v2
	v_mov_b32_e32 v59, v2
	v_mov_b32_e32 v60, v2
	v_mov_b32_e32 v61, v2
	v_mov_b32_e32 v62, v2
	v_mov_b32_e32 v63, v2
	v_mov_b32_e32 v64, v2
	v_mov_b32_e32 v65, v2
	s_waitcnt lgkmcnt(0)
	s_barrier
	v_writelane_b32 v255, s88, 24
	v_writelane_b32 v255, s89, 25
	v_writelane_b32 v255, s90, 26
	v_writelane_b32 v255, s91, 27
	v_writelane_b32 v255, s92, 28
	v_writelane_b32 v255, s93, 29
	v_writelane_b32 v255, s94, 30
	v_writelane_b32 v255, s95, 31
	v_readfirstlane_b32 s88, v68
	v_readfirstlane_b32 s89, v69
	v_readfirstlane_b32 s90, v66
	v_readfirstlane_b32 s91, v67
	v_lshl_add_u32 v161, v163, 4, 16
	s_and_b32 s88, s88, 0xffffff80
	s_and_b32 s90, s90, 0xffffff80
	v_readfirstlane_b32 s93, v161
	v_subrev_u32_e32 v89, s88, v68
	v_subrev_u32_e32 v153, s90, v66
	v_add_u32_e32 v150, 0x10000, v89
	v_add_u32_e32 v154, 0x10000, v153
	v_add_u32_e32 v151, 0x20000, v89
	v_add_u32_e32 v155, 0x20000, v153
	v_add_u32_e32 v152, 0x30000, v89
	v_add_u32_e32 v156, 0x30000, v153
	s_add_u32 s94, s93, 0x4000
	s_add_u32 s88, s88, 0x8688080
	s_addc_u32 s89, s89, 0
	s_add_u32 s90, s90, 0x23a8080
	s_addc_u32 s91, s91, 0
	v_and_b32_e32 v161, 15, v163
	v_lshlrev_b32_e32 v161, 7, v161
	v_bfe_u32 v164, v163, 4, 2
	v_and_b32_e32 v165, 7, v163
	v_xor_b32_e32 v164, v164, v165
	v_lshlrev_b32_e32 v165, 4, v164
	v_xor_b32_e32 v164, 4, v164
	v_lshlrev_b32_e32 v164, 4, v164
	v_lshrrev_b32_e32 v157, 7, v163
	v_lshl_add_u32 v157, v157, 13, v161
	v_add_u32_e32 v157, 16, v157
	v_bfe_u32 v159, v163, 6, 1
	v_lshl_add_u32 v159, v159, 13, v161
	v_add_u32_e32 v159, 16, v159
	v_add_u32_e32 v158, v157, v164
	v_add_u32_e32 v160, v159, v164
	v_add_u32_e32 v157, v157, v165
	v_add_u32_e32 v159, v159, v165
	s_mov_b32 m0, s94
	s_nop 0
	global_load_lds_dwordx4 v89, s[88:89]
	s_add_u32 m0, m0, 0x1000
	s_nop 0
	global_load_lds_dwordx4 v150, s[88:89]
	s_add_u32 m0, m0, 0x1000
	s_nop 0
	global_load_lds_dwordx4 v151, s[88:89]
	s_add_u32 m0, m0, 0x1000
	s_nop 0
	global_load_lds_dwordx4 v152, s[88:89]
	s_add_u32 m0, m0, 0x5000
	s_nop 0
	global_load_lds_dwordx4 v153, s[90:91]
	s_add_u32 m0, m0, 0x1000
	s_nop 0
	global_load_lds_dwordx4 v154, s[90:91]
	s_add_u32 m0, m0, 0x1000
	s_nop 0
	global_load_lds_dwordx4 v155, s[90:91]
	s_add_u32 m0, m0, 0x1000
	s_nop 0
	global_load_lds_dwordx4 v156, s[90:91]
	s_add_u32 s88, s88, 0x80
	s_addc_u32 s89, s89, 0
	s_add_u32 s90, s90, 0x80
	s_addc_u32 s91, s91, 0
	ds_read_b128 v[70:73], v157
	ds_read_b128 v[90:93], v157 offset:2048
	ds_read_b128 v[94:97], v157 offset:4096
	ds_read_b128 v[98:101], v157 offset:6144
	ds_read_b128 v[102:105], v159 offset:32768
	ds_read_b128 v[106:109], v159 offset:34816
	ds_read_b128 v[110:113], v159 offset:36864
	ds_read_b128 v[114:117], v159 offset:38912
	s_movk_i32 s92, 7
; #define G_MMA(ks_) __builtin_amdgcn_s_setprio(1); _Pragma("unroll") for (int m = 0; m < 4; ++m) \
;         _Pragma("unroll") for (int n = 0; n < 4; ++n) acc[m][n] = __builtin_amdgcn_mfma_f32_16x16x32_bf16(bfv##ks_[n], af##ks_[m], acc[m][n], 0, 0, 0); __builtin_amdgcn_s_setprio(0);
; template <class Epi>
; DEV void gemm_tile(const bf16_t* __restrict__ A, int lda, const bf16_t* __restrict__ Bt, int ldb, int K, int tm, int tn, char* smem, const Epi& epi) {
;     ...
;     const int nk = K >> 6;
;     G_DMA(0, 0);
;     asm volatile("s_waitcnt vmcnt(0)" ::: "memory");
;     __syncthreads();
; #pragma unroll 4
;     for (int kt = 0; kt < nk; ++kt) {
;         const int cur = kt & 1;
;         if (kt + 1 < nk) G_DMA(cur ^ 1, kt + 1);
;         {
;             G_FRAGS(cur, 0)
;             G_MMA(0)
;             G_FRAGS(cur, 1)
;             G_MMA(1)
;         }
;         asm volatile("s_waitcnt vmcnt(0)" ::: "memory");
;         __syncthreads();
.Lgemm_in_loop:
	ds_read_b128 v[118:121], v158
	ds_read_b128 v[122:125], v158 offset:2048
	ds_read_b128 v[126:129], v158 offset:4096
	ds_read_b128 v[130:133], v158 offset:6144
	ds_read_b128 v[134:137], v160 offset:32768
	ds_read_b128 v[138:141], v160 offset:34816
	ds_read_b128 v[142:145], v160 offset:36864
	ds_read_b128 v[146:149], v160 offset:38912
	s_setprio 1
	s_waitcnt lgkmcnt(8)
	v_mfma_f32_16x16x32_bf16 v[2:5], v[102:105], v[70:73], v[2:5]
	v_mfma_f32_16x16x32_bf16 v[6:9], v[106:109], v[70:73], v[6:9]
	v_mfma_f32_16x16x32_bf16 v[10:13], v[110:113], v[70:73], v[10:13]
	v_mfma_f32_16x16x32_bf16 v[14:17], v[114:117], v[70:73], v[14:17]
	v_mfma_f32_16x16x32_bf16 v[18:21], v[102:105], v[90:93], v[18:21]
	v_mfma_f32_16x16x32_bf16 v[22:25], v[106:109], v[90:93], v[22:25]
	v_mfma_f32_16x16x32_bf16 v[26:29], v[110:113], v[90:93], v[26:29]
	v_mfma_f32_16x16x32_bf16 v[30:33], v[114:117], v[90:93], v[30:33]
	v_mfma_f32_16x16x32_bf16 v[34:37], v[102:105], v[94:97], v[34:37]
	v_mfma_f32_16x16x32_bf16 v[38:41], v[106:109], v[94:97], v[38:41]
	v_mfma_f32_16x16x32_bf16 v[42:45], v[110:113], v[94:97], v[42:45]
	v_mfma_f32_16x16x32_bf16 v[46:49], v[114:117], v[94:97], v[46:49]
	v_mfma_f32_16x16x32_bf16 v[50:53], v[102:105], v[98:101], v[50:53]
	v_mfma_f32_16x16x32_bf16 v[54:57], v[106:109], v[98:101], v[54:57]
	v_mfma_f32_16x16x32_bf16 v[58:61], v[110:113], v[98:101], v[58:61]
	v_mfma_f32_16x16x32_bf16 v[62:65], v[114:117], v[98:101], v[62:65]
	s_setprio 0
	s_waitcnt vmcnt(0) lgkmcnt(0)
	s_barrier
	ds_read_b128 v[70:73], v157 offset:16384
	ds_read_b128 v[90:93], v157 offset:18432
	ds_read_b128 v[94:97], v157 offset:20480
	ds_read_b128 v[98:101], v157 offset:22528
	ds_read_b128 v[102:105], v159 offset:49152
	ds_read_b128 v[106:109], v159 offset:51200
	ds_read_b128 v[110:113], v159 offset:53248
	ds_read_b128 v[114:117], v159 offset:55296
	s_setprio 1
	s_mov_b32 m0, s93
	v_mfma_f32_16x16x32_bf16 v[2:5], v[134:137], v[118:121], v[2:5]
	global_load_lds_dwordx4 v89, s[88:89]
	s_add_u32 m0, m0, 0x1000
	v_mfma_f32_16x16x32_bf16 v[6:9], v[138:141], v[118:121], v[6:9]
	global_load_lds_dwordx4 v150, s[88:89]
	s_add_u32 m0, m0, 0x1000
	v_mfma_f32_16x16x32_bf16 v[10:13], v[142:145], v[118:121], v[10:13]
	global_load_lds_dwordx4 v151, s[88:89]
	s_add_u32 m0, m0, 0x1000
	v_mfma_f32_16x16x32_bf16 v[14:17], v[146:149], v[118:121], v[14:17]
	global_load_lds_dwordx4 v152, s[88:89]
	s_add_u32 m0, m0, 0x5000
	v_mfma_f32_16x16x32_bf16 v[18:21], v[134:137], v[122:125], v[18:21]
	global_load_lds_dwordx4 v153, s[90:91]
	s_add_u32 m0, m0, 0x1000
	v_mfma_f32_16x16x32_bf16 v[22:25], v[138:141], v[122:125], v[22:25]
	global_load_lds_dwordx4 v154, s[90:91]
	s_add_u32 m0, m0, 0x1000
	v_mfma_f32_16x16x32_bf16 v[26:29], v[142:145], v[122:125], v[26:29]
	global_load_lds_dwordx4 v155, s[90:91]
	s_add_u32 m0, m0, 0x1000
	v_mfma_f32_16x16x32_bf16 v[30:33], v[146:149], v[122:125], v[30:33]
	global_load_lds_dwordx4 v156, s[90:91]
	v_mfma_f32_16x16x32_bf16 v[34:37], v[134:137], v[126:129], v[34:37]
	s_add_u32 s88, s88, 0x80
	v_mfma_f32_16x16x32_bf16 v[38:41], v[138:141], v[126:129], v[38:41]
	s_addc_u32 s89, s89, 0
	v_mfma_f32_16x16x32_bf16 v[42:45], v[142:145], v[126:129], v[42:45]
	s_add_u32 s90, s90, 0x80
	v_mfma_f32_16x16x32_bf16 v[46:49], v[146:149], v[126:129], v[46:49]
	s_addc_u32 s91, s91, 0
	v_mfma_f32_16x16x32_bf16 v[50:53], v[134:137], v[130:133], v[50:53]
	v_mfma_f32_16x16x32_bf16 v[54:57], v[138:141], v[130:133], v[54:57]
	v_mfma_f32_16x16x32_bf16 v[58:61], v[142:145], v[130:133], v[58:61]
	v_mfma_f32_16x16x32_bf16 v[62:65], v[146:149], v[130:133], v[62:65]
	s_setprio 0
	ds_read_b128 v[118:121], v158 offset:16384
	ds_read_b128 v[122:125], v158 offset:18432
	ds_read_b128 v[126:129], v158 offset:20480
	ds_read_b128 v[130:133], v158 offset:22528
	ds_read_b128 v[134:137], v160 offset:49152
	ds_read_b128 v[138:141], v160 offset:51200
	ds_read_b128 v[142:145], v160 offset:53248
	ds_read_b128 v[146:149], v160 offset:55296
	s_setprio 1
	s_waitcnt lgkmcnt(8)
	v_mfma_f32_16x16x32_bf16 v[2:5], v[102:105], v[70:73], v[2:5]
	v_mfma_f32_16x16x32_bf16 v[6:9], v[106:109], v[70:73], v[6:9]
	v_mfma_f32_16x16x32_bf16 v[10:13], v[110:113], v[70:73], v[10:13]
	v_mfma_f32_16x16x32_bf16 v[14:17], v[114:117], v[70:73], v[14:17]
	v_mfma_f32_16x16x32_bf16 v[18:21], v[102:105], v[90:93], v[18:21]
	v_mfma_f32_16x16x32_bf16 v[22:25], v[106:109], v[90:93], v[22:25]
	v_mfma_f32_16x16x32_bf16 v[26:29], v[110:113], v[90:93], v[26:29]
	v_mfma_f32_16x16x32_bf16 v[30:33], v[114:117], v[90:93], v[30:33]
	v_mfma_f32_16x16x32_bf16 v[34:37], v[102:105], v[94:97], v[34:37]
	v_mfma_f32_16x16x32_bf16 v[38:41], v[106:109], v[94:97], v[38:41]
	v_mfma_f32_16x16x32_bf16 v[42:45], v[110:113], v[94:97], v[42:45]
	v_mfma_f32_16x16x32_bf16 v[46:49], v[114:117], v[94:97], v[46:49]
	v_mfma_f32_16x16x32_bf16 v[50:53], v[102:105], v[98:101], v[50:53]
	v_mfma_f32_16x16x32_bf16 v[54:57], v[106:109], v[98:101], v[54:57]
	v_mfma_f32_16x16x32_bf16 v[58:61], v[110:113], v[98:101], v[58:61]
	v_mfma_f32_16x16x32_bf16 v[62:65], v[114:117], v[98:101], v[62:65]
	s_setprio 0
	s_waitcnt vmcnt(0) lgkmcnt(0)
	s_barrier
; #define G_MMA(ks_) __builtin_amdgcn_s_setprio(1); _Pragma("unroll") for (int m = 0; m < 4; ++m) \
;         _Pragma("unroll") for (int n = 0; n < 4; ++n) acc[m][n] = __builtin_amdgcn_mfma_f32_16x16x32_bf16(bfv##ks_[n], af##ks_[m], acc[m][n], 0, 0, 0); __builtin_amdgcn_s_setprio(0);
; template <class Epi>
; DEV void gemm_tile(const bf16_t* __restrict__ A, int lda, const bf16_t* __restrict__ Bt, int ldb, int K, int tm, int tn, char* smem, const Epi& epi) {
;     ...
;     const int nk = K >> 6;
;     G_DMA(0, 0);
;     asm volatile("s_waitcnt vmcnt(0)" ::: "memory");
;     __syncthreads();
; #pragma unroll 4
;     for (int kt = 0; kt < nk; ++kt) {
;         const int cur = kt & 1;
;         if (kt + 1 < nk) G_DMA(cur ^ 1, kt + 1);
;         {
;             G_FRAGS(cur, 0)
;             G_MMA(0)
;             G_FRAGS(cur, 1)
;             G_MMA(1)
;         }
;         asm volatile("s_waitcnt vmcnt(0)" ::: "memory");
;         __syncthreads();
	ds_read_b128 v[70:73], v157
	ds_read_b128 v[90:93], v157 offset:2048
	ds_read_b128 v[94:97], v157 offset:4096
	ds_read_b128 v[98:101], v157 offset:6144
	ds_read_b128 v[102:105], v159 offset:32768
	ds_read_b128 v[106:109], v159 offset:34816
	ds_read_b128 v[110:113], v159 offset:36864
	ds_read_b128 v[114:117], v159 offset:38912
	s_setprio 1
	s_mov_b32 m0, s94
	v_mfma_f32_16x16x32_bf16 v[2:5], v[134:137], v[118:121], v[2:5]
	global_load_lds_dwordx4 v89, s[88:89]
	s_add_u32 m0, m0, 0x1000
	v_mfma_f32_16x16x32_bf16 v[6:9], v[138:141], v[118:121], v[6:9]
	global_load_lds_dwordx4 v150, s[88:89]
	s_add_u32 m0, m0, 0x1000
	v_mfma_f32_16x16x32_bf16 v[10:13], v[142:145], v[118:121], v[10:13]
	global_load_lds_dwordx4 v151, s[88:89]
	s_add_u32 m0, m0, 0x1000
	v_mfma_f32_16x16x32_bf16 v[14:17], v[146:149], v[118:121], v[14:17]
	global_load_lds_dwordx4 v152, s[88:89]
	s_add_u32 m0, m0, 0x5000
	v_mfma_f32_16x16x32_bf16 v[18:21], v[134:137], v[122:125], v[18:21]
	global_load_lds_dwordx4 v153, s[90:91]
	s_add_u32 m0, m0, 0x1000
	v_mfma_f32_16x16x32_bf16 v[22:25], v[138:141], v[122:125], v[22:25]
	global_load_lds_dwordx4 v154, s[90:91]
	s_add_u32 m0, m0, 0x1000
	v_mfma_f32_16x16x32_bf16 v[26:29], v[142:145], v[122:125], v[26:29]
	global_load_lds_dwordx4 v155, s[90:91]
	s_add_u32 m0, m0, 0x1000
	v_mfma_f32_16x16x32_bf16 v[30:33], v[146:149], v[122:125], v[30:33]
	global_load_lds_dwordx4 v156, s[90:91]
	v_mfma_f32_16x16x32_bf16 v[34:37], v[134:137], v[126:129], v[34:37]
	s_add_u32 s88, s88, 0x80
	v_mfma_f32_16x16x32_bf16 v[38:41], v[138:141], v[126:129], v[38:41]
	s_addc_u32 s89, s89, 0
	v_mfma_f32_16x16x32_bf16 v[42:45], v[142:145], v[126:129], v[42:45]
	s_add_u32 s90, s90, 0x80
	v_mfma_f32_16x16x32_bf16 v[46:49], v[146:149], v[126:129], v[46:49]
	s_addc_u32 s91, s91, 0
	v_mfma_f32_16x16x32_bf16 v[50:53], v[134:137], v[130:133], v[50:53]
	v_mfma_f32_16x16x32_bf16 v[54:57], v[138:141], v[130:133], v[54:57]
	v_mfma_f32_16x16x32_bf16 v[58:61], v[142:145], v[130:133], v[58:61]
	v_mfma_f32_16x16x32_bf16 v[62:65], v[146:149], v[130:133], v[62:65]
	s_setprio 0
	s_sub_u32 s92, s92, 1
	s_cmp_lg_u32 s92, 0
	s_cbranch_scc1 .Lgemm_in_loop
	ds_read_b128 v[118:121], v158
	ds_read_b128 v[122:125], v158 offset:2048
	ds_read_b128 v[126:129], v158 offset:4096
	ds_read_b128 v[130:133], v158 offset:6144
	ds_read_b128 v[134:137], v160 offset:32768
	ds_read_b128 v[138:141], v160 offset:34816
	ds_read_b128 v[142:145], v160 offset:36864
	ds_read_b128 v[146:149], v160 offset:38912
	s_setprio 1
	s_waitcnt lgkmcnt(8)
	v_mfma_f32_16x16x32_bf16 v[2:5], v[102:105], v[70:73], v[2:5]
	v_mfma_f32_16x16x32_bf16 v[6:9], v[106:109], v[70:73], v[6:9]
	v_mfma_f32_16x16x32_bf16 v[10:13], v[110:113], v[70:73], v[10:13]
	v_mfma_f32_16x16x32_bf16 v[14:17], v[114:117], v[70:73], v[14:17]
	v_mfma_f32_16x16x32_bf16 v[18:21], v[102:105], v[90:93], v[18:21]
	v_mfma_f32_16x16x32_bf16 v[22:25], v[106:109], v[90:93], v[22:25]
	v_mfma_f32_16x16x32_bf16 v[26:29], v[110:113], v[90:93], v[26:29]
	v_mfma_f32_16x16x32_bf16 v[30:33], v[114:117], v[90:93], v[30:33]
	v_mfma_f32_16x16x32_bf16 v[34:37], v[102:105], v[94:97], v[34:37]
	v_mfma_f32_16x16x32_bf16 v[38:41], v[106:109], v[94:97], v[38:41]
	v_mfma_f32_16x16x32_bf16 v[42:45], v[110:113], v[94:97], v[42:45]
	v_mfma_f32_16x16x32_bf16 v[46:49], v[114:117], v[94:97], v[46:49]
	v_mfma_f32_16x16x32_bf16 v[50:53], v[102:105], v[98:101], v[50:53]
	v_mfma_f32_16x16x32_bf16 v[54:57], v[106:109], v[98:101], v[54:57]
	v_mfma_f32_16x16x32_bf16 v[58:61], v[110:113], v[98:101], v[58:61]
	v_mfma_f32_16x16x32_bf16 v[62:65], v[114:117], v[98:101], v[62:65]
	s_setprio 0
	s_waitcnt vmcnt(0) lgkmcnt(0)
	s_barrier
; #define G_MMA(ks_) __builtin_amdgcn_s_setprio(1); _Pragma("unroll") for (int m = 0; m < 4; ++m) \
;         _Pragma("unroll") for (int n = 0; n < 4; ++n) acc[m][n] = __builtin_amdgcn_mfma_f32_16x16x32_bf16(bfv##ks_[n], af##ks_[m], acc[m][n], 0, 0, 0); __builtin_amdgcn_s_setprio(0);
; template <class Epi>
; DEV void gemm_tile(const bf16_t* __restrict__ A, int lda, const bf16_t* __restrict__ Bt, int ldb, int K, int tm, int tn, char* smem, const Epi& epi) {
;     ...
;     const int nk = K >> 6;
;     G_DMA(0, 0);
;     asm volatile("s_waitcnt vmcnt(0)" ::: "memory");
;     __syncthreads();
; #pragma unroll 4
;     for (int kt = 0; kt < nk; ++kt) {
;         const int cur = kt & 1;
;         if (kt + 1 < nk) G_DMA(cur ^ 1, kt + 1);
;         {
;             G_FRAGS(cur, 0)
;             G_MMA(0)
;             G_FRAGS(cur, 1)
;             G_MMA(1)
;         }
;         asm volatile("s_waitcnt vmcnt(0)" ::: "memory");
;         __syncthreads();
;     }
	ds_read_b128 v[70:73], v157 offset:16384
	ds_read_b128 v[90:93], v157 offset:18432
	ds_read_b128 v[94:97], v157 offset:20480
	ds_read_b128 v[98:101], v157 offset:22528
	ds_read_b128 v[102:105], v159 offset:49152
	ds_read_b128 v[106:109], v159 offset:51200
	ds_read_b128 v[110:113], v159 offset:53248
	ds_read_b128 v[114:117], v159 offset:55296
	s_setprio 1
	v_mfma_f32_16x16x32_bf16 v[2:5], v[134:137], v[118:121], v[2:5]
	v_mfma_f32_16x16x32_bf16 v[6:9], v[138:141], v[118:121], v[6:9]
	v_mfma_f32_16x16x32_bf16 v[10:13], v[142:145], v[118:121], v[10:13]
	v_mfma_f32_16x16x32_bf16 v[14:17], v[146:149], v[118:121], v[14:17]
	v_mfma_f32_16x16x32_bf16 v[18:21], v[134:137], v[122:125], v[18:21]
	v_mfma_f32_16x16x32_bf16 v[22:25], v[138:141], v[122:125], v[22:25]
	v_mfma_f32_16x16x32_bf16 v[26:29], v[142:145], v[122:125], v[26:29]
	v_mfma_f32_16x16x32_bf16 v[30:33], v[146:149], v[122:125], v[30:33]
	v_mfma_f32_16x16x32_bf16 v[34:37], v[134:137], v[126:129], v[34:37]
	v_mfma_f32_16x16x32_bf16 v[38:41], v[138:141], v[126:129], v[38:41]
	v_mfma_f32_16x16x32_bf16 v[42:45], v[142:145], v[126:129], v[42:45]
	v_mfma_f32_16x16x32_bf16 v[46:49], v[146:149], v[126:129], v[46:49]
	v_mfma_f32_16x16x32_bf16 v[50:53], v[134:137], v[130:133], v[50:53]
	v_mfma_f32_16x16x32_bf16 v[54:57], v[138:141], v[130:133], v[54:57]
	v_mfma_f32_16x16x32_bf16 v[58:61], v[142:145], v[130:133], v[58:61]
	v_mfma_f32_16x16x32_bf16 v[62:65], v[146:149], v[130:133], v[62:65]
	s_setprio 0
	ds_read_b128 v[118:121], v158 offset:16384
	ds_read_b128 v[122:125], v158 offset:18432
	ds_read_b128 v[126:129], v158 offset:20480
	ds_read_b128 v[130:133], v158 offset:22528
	ds_read_b128 v[134:137], v160 offset:49152
	ds_read_b128 v[138:141], v160 offset:51200
	ds_read_b128 v[142:145], v160 offset:53248
	ds_read_b128 v[146:149], v160 offset:55296
	s_setprio 1
	s_waitcnt lgkmcnt(8)
	v_mfma_f32_16x16x32_bf16 v[2:5], v[102:105], v[70:73], v[2:5]
	v_mfma_f32_16x16x32_bf16 v[6:9], v[106:109], v[70:73], v[6:9]
	v_mfma_f32_16x16x32_bf16 v[10:13], v[110:113], v[70:73], v[10:13]
	v_mfma_f32_16x16x32_bf16 v[14:17], v[114:117], v[70:73], v[14:17]
	v_mfma_f32_16x16x32_bf16 v[18:21], v[102:105], v[90:93], v[18:21]
	v_mfma_f32_16x16x32_bf16 v[22:25], v[106:109], v[90:93], v[22:25]
	v_mfma_f32_16x16x32_bf16 v[26:29], v[110:113], v[90:93], v[26:29]
	v_mfma_f32_16x16x32_bf16 v[30:33], v[114:117], v[90:93], v[30:33]
	v_mfma_f32_16x16x32_bf16 v[34:37], v[102:105], v[94:97], v[34:37]
	v_mfma_f32_16x16x32_bf16 v[38:41], v[106:109], v[94:97], v[38:41]
	v_mfma_f32_16x16x32_bf16 v[42:45], v[110:113], v[94:97], v[42:45]
	v_mfma_f32_16x16x32_bf16 v[46:49], v[114:117], v[94:97], v[46:49]
	v_mfma_f32_16x16x32_bf16 v[50:53], v[102:105], v[98:101], v[50:53]
	v_mfma_f32_16x16x32_bf16 v[54:57], v[106:109], v[98:101], v[54:57]
	v_mfma_f32_16x16x32_bf16 v[58:61], v[110:113], v[98:101], v[58:61]
	v_mfma_f32_16x16x32_bf16 v[62:65], v[114:117], v[98:101], v[62:65]
	s_setprio 0
	s_waitcnt lgkmcnt(0)
	s_barrier
	s_setprio 1
	v_mfma_f32_16x16x32_bf16 v[2:5], v[134:137], v[118:121], v[2:5]
	v_mfma_f32_16x16x32_bf16 v[6:9], v[138:141], v[118:121], v[6:9]
	v_mfma_f32_16x16x32_bf16 v[10:13], v[142:145], v[118:121], v[10:13]
	v_mfma_f32_16x16x32_bf16 v[14:17], v[146:149], v[118:121], v[14:17]
	v_mfma_f32_16x16x32_bf16 v[18:21], v[134:137], v[122:125], v[18:21]
	v_mfma_f32_16x16x32_bf16 v[22:25], v[138:141], v[122:125], v[22:25]
	v_mfma_f32_16x16x32_bf16 v[26:29], v[142:145], v[122:125], v[26:29]
	v_mfma_f32_16x16x32_bf16 v[30:33], v[146:149], v[122:125], v[30:33]
	v_mfma_f32_16x16x32_bf16 v[34:37], v[134:137], v[126:129], v[34:37]
	v_mfma_f32_16x16x32_bf16 v[38:41], v[138:141], v[126:129], v[38:41]
	v_mfma_f32_16x16x32_bf16 v[42:45], v[142:145], v[126:129], v[42:45]
	v_mfma_f32_16x16x32_bf16 v[46:49], v[146:149], v[126:129], v[46:49]
	v_mfma_f32_16x16x32_bf16 v[50:53], v[134:137], v[130:133], v[50:53]
	v_mfma_f32_16x16x32_bf16 v[54:57], v[138:141], v[130:133], v[54:57]
	v_mfma_f32_16x16x32_bf16 v[58:61], v[142:145], v[130:133], v[58:61]
	v_mfma_f32_16x16x32_bf16 v[62:65], v[146:149], v[130:133], v[62:65]
	s_setprio 0
	v_readlane_b32 s88, v255, 24
	v_readlane_b32 s89, v255, 25
	v_readlane_b32 s90, v255, 26
	v_readlane_b32 s91, v255, 27
	v_readlane_b32 s92, v255, 28
	v_readlane_b32 s93, v255, 29
	v_readlane_b32 s94, v255, 30
	v_readlane_b32 s95, v255, 31
	s_nop 7
	s_nop 1
